# GEMM-phase barriers: weight-conversion stores made write-through (sc1) like the epilogues, L2 write-back dropped from the release of the three barriers that end GEMM phases
# speedup vs baseline: 1.0147x; 1.0085x over previous
.LBB0_415:
	s_addk_i32 s15, 0x200
	s_cmpk_lt_i32 s15, 0x580
	s_movk_i32 s4, 0x1b80
	s_cselect_b32 s4, 0x1600, s4
	v_readlane_b32 s5, v255, 19
	s_add_i32 s4, s5, s4
	s_add_i32 s5, s15, s4
	s_mul_hi_i32 s4, s5, 0x66666667
	s_lshr_b32 s6, s4, 31
	s_ashr_i32 s4, s4, 12
	s_add_i32 s4, s4, s6
	s_mul_i32 s6, s4, 0x2800
	s_sub_i32 s16, s5, s6
	s_cmpk_gt_i32 s16, 0x20ff
	s_mov_b64 s[6:7], -1
	s_cbranch_scc0 .LBB0_421
	s_cmpk_gt_u32 s16, 0x25ff
	s_cbranch_scc0 .LBB0_418
	s_load_dwordx2 s[6:7], s[8:9], 0x78
	s_ashr_i32 s5, s4, 31
	s_lshl_b64 s[18:19], s[4:5], 22
	v_lshlrev_b32_e32 v0, 2, v2
	v_mov_b32_e32 v41, v1
	s_waitcnt lgkmcnt(0)
	s_add_u32 s17, s6, s18
	s_addc_u32 s18, s7, s19
	s_lshl_b64 s[6:7], s[4:5], 21
	s_add_u32 s19, s0, s6
	s_addc_u32 s20, s1, s7
	s_lshl_b32 s5, s16, 1
	s_and_b32 s5, s5, 0x7fffffc0
	s_add_i32 s44, s5, 0xffffb400
	s_lshl_b32 s5, s16, 5
	s_and_b32 s5, s5, 0x3e0
	s_lshl_b32 s6, s5, 2
	s_add_u32 s6, s17, s6
	v_or_b32_e32 v40, s44, v5
	s_addc_u32 s7, s18, 0
	v_lshl_add_u64 v[42:43], s[6:7], 0, v[0:1]
	v_lshlrev_b64 v[6:7], 12, v[40:41]
	v_or_b32_e32 v0, 8, v40
	v_lshl_add_u64 v[6:7], v[42:43], 0, v[6:7]
	v_lshlrev_b64 v[16:17], 12, v[0:1]
	global_load_dwordx4 v[6:9], v[6:7], off nt
	v_lshl_add_u64 v[16:17], v[42:43], 0, v[16:17]
	v_or_b32_e32 v0, 16, v40
	global_load_dwordx4 v[16:19], v[16:17], off nt
	v_lshlrev_b64 v[20:21], 12, v[0:1]
	v_lshl_add_u64 v[20:21], v[42:43], 0, v[20:21]
	v_or_b32_e32 v0, 24, v40
	global_load_dwordx4 v[20:23], v[20:21], off nt
	v_lshlrev_b64 v[24:25], 12, v[0:1]
	v_lshl_add_u64 v[24:25], v[42:43], 0, v[24:25]
	v_or_b32_e32 v0, 32, v40
	global_load_dwordx4 v[24:27], v[24:25], off nt
	v_lshlrev_b64 v[28:29], 12, v[0:1]
	v_lshl_add_u64 v[28:29], v[42:43], 0, v[28:29]
	v_or_b32_e32 v0, 40, v40
	global_load_dwordx4 v[28:31], v[28:29], off nt
	v_lshlrev_b64 v[32:33], 12, v[0:1]
	v_lshl_add_u64 v[32:33], v[42:43], 0, v[32:33]
	v_or_b32_e32 v0, 48, v40
	global_load_dwordx4 v[32:35], v[32:33], off nt
	v_lshlrev_b64 v[36:37], 12, v[0:1]
	v_lshl_add_u64 v[36:37], v[42:43], 0, v[36:37]
	v_or_b32_e32 v0, 56, v40
	global_load_dwordx4 v[36:39], v[36:37], off nt
	v_lshlrev_b64 v[40:41], 12, v[0:1]
	v_lshl_add_u64 v[40:41], v[42:43], 0, v[40:41]
	global_load_dwordx4 v[40:43], v[40:41], off nt
	v_add_u32_e32 v0, v10, v11
	s_lshl_b64 s[6:7], s[44:45], 1
	s_add_u32 s6, s19, s6
	s_addc_u32 s7, s20, s7
	s_waitcnt vmcnt(0)
	ds_write2_b32 v0, v6, v7 offset1:1
	ds_write2_b32 v0, v8, v9 offset0:2 offset1:3
	v_add_u32_e32 v6, 0x420, v0
	ds_write2_b32 v6, v16, v17 offset1:1
	v_add_u32_e32 v6, 0x428, v0
	ds_write2_b32 v6, v18, v19 offset1:1
	v_add_u32_e32 v6, 0x840, v0
	ds_write2_b32 v6, v20, v21 offset1:1
	v_add_u32_e32 v6, 0x848, v0
	ds_write2_b32 v6, v22, v23 offset1:1
	v_add_u32_e32 v6, 0xc60, v0
	ds_write2_b32 v6, v24, v25 offset1:1
	v_add_u32_e32 v6, 0xc68, v0
	ds_write2_b32 v6, v26, v27 offset1:1
	v_add_u32_e32 v6, 0x1080, v0
	ds_write2_b32 v6, v28, v29 offset1:1
	v_add_u32_e32 v6, 0x1088, v0
	ds_write2_b32 v6, v30, v31 offset1:1
	v_add_u32_e32 v6, 0x14a0, v0
	ds_write2_b32 v6, v32, v33 offset1:1
	v_add_u32_e32 v6, 0x14a8, v0
	ds_write2_b32 v6, v34, v35 offset1:1
	v_add_u32_e32 v6, 0x18c0, v0
	ds_write2_b32 v6, v36, v37 offset1:1
	v_add_u32_e32 v6, 0x18c8, v0
	ds_write2_b32 v6, v38, v39 offset1:1
	v_add_u32_e32 v6, 0x1ce0, v0
	v_add_u32_e32 v0, 0x1ce8, v0
	ds_write2_b32 v6, v40, v41 offset1:1
	ds_write2_b32 v0, v42, v43 offset1:1
	s_waitcnt lgkmcnt(0)
	ds_read2_b32 v[8:9], v15 offset0:33 offset1:41
	ds_read2_b32 v[20:21], v15 offset1:8
	v_lshlrev_b32_e32 v0, 1, v4
	ds_read2_b32 v[22:23], v15 offset0:66 offset1:74
	ds_read2_b32 v[24:25], v15 offset0:99 offset1:107
	v_lshl_add_u64 v[6:7], s[6:7], 0, v[0:1]
	s_waitcnt lgkmcnt(3)
	v_bfe_u32 v16, v8, 16, 1
	s_waitcnt lgkmcnt(2)
	v_bfe_u32 v0, v20, 16, 1
	v_add3_u32 v0, v20, v0, s60
	v_lshrrev_b32_e32 v0, 16, v0
	v_add3_u32 v8, v8, v16, s60
	ds_read2_b32 v[26:27], v15 offset0:132 offset1:140
	ds_read2_b32 v[28:29], v15 offset0:165 offset1:173
	v_and_or_b32 v16, v8, s85, v0
	s_waitcnt lgkmcnt(3)
	v_bfe_u32 v0, v22, 16, 1
	v_add3_u32 v0, v22, v0, s60
	s_waitcnt lgkmcnt(2)
	v_bfe_u32 v8, v24, 16, 1
	v_lshrrev_b32_e32 v0, 16, v0
	v_add3_u32 v8, v24, v8, s60
	ds_read2_b32 v[30:31], v15 offset0:198 offset1:206
	ds_read2_b32 v[32:33], v15 offset0:231 offset1:239
	v_and_or_b32 v17, v8, s85, v0
	s_waitcnt lgkmcnt(3)
	v_bfe_u32 v0, v26, 16, 1
	v_add3_u32 v0, v26, v0, s60
	s_waitcnt lgkmcnt(2)
	v_bfe_u32 v8, v28, 16, 1
	v_lshrrev_b32_e32 v0, 16, v0
	v_add3_u32 v8, v28, v8, s60
	v_and_or_b32 v18, v8, s85, v0
	s_waitcnt lgkmcnt(1)
	v_bfe_u32 v0, v30, 16, 1
	v_add3_u32 v0, v30, v0, s60
	s_waitcnt lgkmcnt(0)
	v_bfe_u32 v8, v32, 16, 1
	v_lshrrev_b32_e32 v0, 16, v0
	v_add3_u32 v8, v32, v8, s60
	v_and_or_b32 v19, v8, s85, v0
	v_or_b32_e32 v0, s5, v5
	v_lshlrev_b32_e32 v0, 11, v0
	v_lshl_add_u64 v[34:35], v[6:7], 0, v[0:1]
	v_bfe_u32 v0, v21, 16, 1
	v_add3_u32 v0, v21, v0, s60
	v_bfe_u32 v8, v9, 16, 1
	v_lshrrev_b32_e32 v0, 16, v0
	v_add3_u32 v8, v9, v8, s60
	global_store_dwordx4 v[34:35], v[16:19], off sc1
	s_mov_b64 s[6:7], 0
	s_nop 0
	v_and_or_b32 v16, v8, s85, v0
	v_bfe_u32 v0, v23, 16, 1
	v_add3_u32 v0, v23, v0, s60
	v_bfe_u32 v8, v25, 16, 1
	v_lshrrev_b32_e32 v0, 16, v0
	v_add3_u32 v8, v25, v8, s60
	v_and_or_b32 v17, v8, s85, v0
	v_bfe_u32 v0, v27, 16, 1
	v_add3_u32 v0, v27, v0, s60
	v_bfe_u32 v8, v29, 16, 1
	v_lshrrev_b32_e32 v0, 16, v0
	v_add3_u32 v8, v29, v8, s60
	v_and_or_b32 v18, v8, s85, v0
	v_bfe_u32 v0, v31, 16, 1
	v_add3_u32 v0, v31, v0, s60
	v_bfe_u32 v8, v33, 16, 1
	v_lshrrev_b32_e32 v0, 16, v0
	v_add3_u32 v8, v33, v8, s60
	v_and_or_b32 v19, v8, s85, v0
	v_or_b32_e32 v0, s5, v12
	v_lshlrev_b32_e32 v0, 11, v0
	v_lshl_add_u64 v[8:9], v[6:7], 0, v[0:1]
	global_store_dwordx4 v[8:9], v[16:19], off sc1
	ds_read2_b32 v[8:9], v15 offset0:49 offset1:57
	ds_read2_b32 v[20:21], v15 offset0:16 offset1:24
	ds_read2_b32 v[22:23], v15 offset0:82 offset1:90
	ds_read2_b32 v[24:25], v15 offset0:115 offset1:123
	ds_read2_b32 v[26:27], v15 offset0:148 offset1:156
	ds_read2_b32 v[28:29], v15 offset0:181 offset1:189
	ds_read2_b32 v[30:31], v15 offset0:214 offset1:222
	ds_read2_b32 v[32:33], v15 offset0:247 offset1:255
	s_waitcnt lgkmcnt(7)
	v_bfe_u32 v16, v8, 16, 1
	s_waitcnt lgkmcnt(6)
	v_bfe_u32 v0, v20, 16, 1
	v_add3_u32 v0, v20, v0, s60
	v_lshrrev_b32_e32 v0, 16, v0
	v_add3_u32 v8, v8, v16, s60
	v_and_or_b32 v16, v8, s85, v0
	s_waitcnt lgkmcnt(5)
	v_bfe_u32 v0, v22, 16, 1
	v_add3_u32 v0, v22, v0, s60
	s_waitcnt lgkmcnt(4)
	v_bfe_u32 v8, v24, 16, 1
	v_lshrrev_b32_e32 v0, 16, v0
	v_add3_u32 v8, v24, v8, s60
	v_and_or_b32 v17, v8, s85, v0
	s_waitcnt lgkmcnt(3)
	v_bfe_u32 v0, v26, 16, 1
	v_add3_u32 v0, v26, v0, s60
	s_waitcnt lgkmcnt(2)
	v_bfe_u32 v8, v28, 16, 1
	v_lshrrev_b32_e32 v0, 16, v0
	v_add3_u32 v8, v28, v8, s60
	v_and_or_b32 v18, v8, s85, v0
	s_waitcnt lgkmcnt(1)
	v_bfe_u32 v0, v30, 16, 1
	v_add3_u32 v0, v30, v0, s60
	s_waitcnt lgkmcnt(0)
	v_bfe_u32 v8, v32, 16, 1
	v_lshrrev_b32_e32 v0, 16, v0
	v_add3_u32 v8, v32, v8, s60
	v_and_or_b32 v19, v8, s85, v0
	v_or_b32_e32 v0, s5, v13
	v_lshlrev_b32_e32 v0, 11, v0
	v_lshl_add_u64 v[34:35], v[6:7], 0, v[0:1]
	v_bfe_u32 v0, v21, 16, 1
	v_add3_u32 v0, v21, v0, s60
	v_bfe_u32 v8, v9, 16, 1
	v_lshrrev_b32_e32 v0, 16, v0
	v_add3_u32 v8, v9, v8, s60
	global_store_dwordx4 v[34:35], v[16:19], off sc1
	s_nop 1
	v_and_or_b32 v16, v8, s85, v0
	v_bfe_u32 v0, v23, 16, 1
	v_add3_u32 v0, v23, v0, s60
	v_bfe_u32 v8, v25, 16, 1
	v_lshrrev_b32_e32 v0, 16, v0
	v_add3_u32 v8, v25, v8, s60
	v_and_or_b32 v17, v8, s85, v0
	v_bfe_u32 v0, v27, 16, 1
	v_add3_u32 v0, v27, v0, s60
	v_bfe_u32 v8, v29, 16, 1
	v_lshrrev_b32_e32 v0, 16, v0
	v_add3_u32 v8, v29, v8, s60
	v_and_or_b32 v18, v8, s85, v0
	v_bfe_u32 v0, v31, 16, 1
	v_add3_u32 v0, v31, v0, s60
	v_bfe_u32 v8, v33, 16, 1
	v_lshrrev_b32_e32 v0, 16, v0
	v_add3_u32 v8, v33, v8, s60
	v_and_or_b32 v19, v8, s85, v0
	v_or_b32_e32 v0, s5, v14
	v_lshlrev_b32_e32 v0, 11, v0
	v_lshl_add_u64 v[6:7], v[6:7], 0, v[0:1]
	global_store_dwordx4 v[6:7], v[16:19], off sc1
	s_waitcnt lgkmcnt(0)
.LBB0_418:
	s_andn2_b64 vcc, exec, s[6:7]
	s_cbranch_vccnz .LBB0_420
	s_add_i32 s5, s16, 0xdf00
	s_and_b32 s6, s5, 0xffff
	s_mul_i32 s6, s6, 0xcccd
	s_lshr_b32 s17, s6, 16
	s_lshr_b32 s6, s6, 22
	s_mulk_i32 s6, 0x50
	s_sub_i32 s5, s5, s6
	s_load_dwordx2 s[6:7], s[8:9], 0x70
	s_mul_i32 s19, s4, 0xa00000
	s_mul_hi_i32 s18, s4, 0xa00000
	v_lshlrev_b32_e32 v0, 2, v2
	s_waitcnt lgkmcnt(0)
	s_add_u32 s6, s6, s19
	s_addc_u32 s7, s7, s18
	s_mul_i32 s19, s4, 0x500000
	s_mul_hi_i32 s18, s4, 0x500000
	s_add_u32 s19, s2, s19
	s_addc_u32 s18, s3, s18
	s_lshl_b32 s5, s5, 5
	s_and_b32 s5, s5, 0xffe0
	s_and_b32 s17, s17, 0xffc0
	s_lshl_b32 s20, s5, 2
	s_add_u32 s6, s6, s20
	v_or_b32_e32 v8, s17, v5
	s_addc_u32 s7, s7, 0
	v_lshl_add_u64 v[6:7], s[6:7], 0, v[0:1]
	v_mul_u32_u24_e32 v0, 0xa00, v8
	v_lshlrev_b32_e32 v0, 2, v0
	v_lshl_add_u64 v[40:41], v[6:7], 0, v[0:1]
	s_mov_b32 s6, 0x14000
	v_add_co_u32_e32 v16, vcc, s6, v40
	global_load_dwordx4 v[6:9], v[40:41], off nt
	s_nop 0
	v_addc_co_u32_e32 v17, vcc, 0, v41, vcc
	s_mov_b32 s6, 0x28000
	global_load_dwordx4 v[16:19], v[16:17], off nt
	v_add_co_u32_e32 v20, vcc, s6, v40
	s_mov_b32 s6, 0x3c000
	s_nop 0
	v_addc_co_u32_e32 v21, vcc, 0, v41, vcc
	global_load_dwordx4 v[20:23], v[20:21], off nt
	v_add_co_u32_e32 v24, vcc, s6, v40
	s_mov_b32 s6, 0x50000
	s_nop 0
	v_addc_co_u32_e32 v25, vcc, 0, v41, vcc
	global_load_dwordx4 v[24:27], v[24:25], off nt
	v_add_co_u32_e32 v28, vcc, s6, v40
	s_mov_b32 s6, 0x64000
	s_nop 0
	v_addc_co_u32_e32 v29, vcc, 0, v41, vcc
	global_load_dwordx4 v[28:31], v[28:29], off nt
	v_add_co_u32_e32 v32, vcc, s6, v40
	s_mov_b32 s6, 0x78000
	s_nop 0
	v_addc_co_u32_e32 v33, vcc, 0, v41, vcc
	global_load_dwordx4 v[32:35], v[32:33], off nt
	v_add_co_u32_e32 v36, vcc, s6, v40
	s_mov_b32 s6, 0x8c000
	s_nop 0
	v_addc_co_u32_e32 v37, vcc, 0, v41, vcc
	global_load_dwordx4 v[36:39], v[36:37], off nt
	v_add_co_u32_e32 v40, vcc, s6, v40
	v_add_u32_e32 v0, v10, v11
	s_nop 0
	v_addc_co_u32_e32 v41, vcc, 0, v41, vcc
	global_load_dwordx4 v[40:43], v[40:41], off nt
	s_lshl_b32 s6, s17, 1
	s_add_u32 s6, s19, s6
	s_addc_u32 s7, s18, 0
	s_waitcnt vmcnt(0)
	ds_write2_b32 v0, v6, v7 offset1:1
	ds_write2_b32 v0, v8, v9 offset0:2 offset1:3
	v_add_u32_e32 v6, 0x420, v0
	ds_write2_b32 v6, v16, v17 offset1:1
	v_add_u32_e32 v6, 0x428, v0
	ds_write2_b32 v6, v18, v19 offset1:1
	v_add_u32_e32 v6, 0x840, v0
	ds_write2_b32 v6, v20, v21 offset1:1
	v_add_u32_e32 v6, 0x848, v0
	ds_write2_b32 v6, v22, v23 offset1:1
	v_add_u32_e32 v6, 0xc60, v0
	ds_write2_b32 v6, v24, v25 offset1:1
	v_add_u32_e32 v6, 0xc68, v0
	ds_write2_b32 v6, v26, v27 offset1:1
	v_add_u32_e32 v6, 0x1080, v0
	ds_write2_b32 v6, v28, v29 offset1:1
	v_add_u32_e32 v6, 0x1088, v0
	ds_write2_b32 v6, v30, v31 offset1:1
	v_add_u32_e32 v6, 0x14a0, v0
	ds_write2_b32 v6, v32, v33 offset1:1
	v_add_u32_e32 v6, 0x14a8, v0
	ds_write2_b32 v6, v34, v35 offset1:1
	v_add_u32_e32 v6, 0x18c0, v0
	ds_write2_b32 v6, v36, v37 offset1:1
	v_add_u32_e32 v6, 0x18c8, v0
	ds_write2_b32 v6, v38, v39 offset1:1
	v_add_u32_e32 v6, 0x1ce0, v0
	v_add_u32_e32 v0, 0x1ce8, v0
	ds_write2_b32 v6, v40, v41 offset1:1
	ds_write2_b32 v0, v42, v43 offset1:1
	s_waitcnt lgkmcnt(0)
	ds_read2_b32 v[8:9], v15 offset0:33 offset1:41
	ds_read2_b32 v[20:21], v15 offset1:8
	v_lshlrev_b32_e32 v0, 1, v4
	ds_read2_b32 v[22:23], v15 offset0:66 offset1:74
	ds_read2_b32 v[24:25], v15 offset0:99 offset1:107
	v_lshl_add_u64 v[6:7], s[6:7], 0, v[0:1]
	s_waitcnt lgkmcnt(3)
	v_bfe_u32 v16, v8, 16, 1
	s_waitcnt lgkmcnt(2)
	v_bfe_u32 v0, v20, 16, 1
	v_add3_u32 v0, v20, v0, s60
	v_lshrrev_b32_e32 v0, 16, v0
	v_add3_u32 v8, v8, v16, s60
	ds_read2_b32 v[26:27], v15 offset0:132 offset1:140
	ds_read2_b32 v[28:29], v15 offset0:165 offset1:173
	v_and_or_b32 v16, v8, s85, v0
	s_waitcnt lgkmcnt(3)
	v_bfe_u32 v0, v22, 16, 1
	v_add3_u32 v0, v22, v0, s60
	s_waitcnt lgkmcnt(2)
	v_bfe_u32 v8, v24, 16, 1
	v_lshrrev_b32_e32 v0, 16, v0
	v_add3_u32 v8, v24, v8, s60
	ds_read2_b32 v[30:31], v15 offset0:198 offset1:206
	ds_read2_b32 v[32:33], v15 offset0:231 offset1:239
	v_and_or_b32 v17, v8, s85, v0
	s_waitcnt lgkmcnt(3)
	v_bfe_u32 v0, v26, 16, 1
	v_add3_u32 v0, v26, v0, s60
	s_waitcnt lgkmcnt(2)
	v_bfe_u32 v8, v28, 16, 1
	v_lshrrev_b32_e32 v0, 16, v0
	v_add3_u32 v8, v28, v8, s60
	v_and_or_b32 v18, v8, s85, v0
	s_waitcnt lgkmcnt(1)
	v_bfe_u32 v0, v30, 16, 1
	v_add3_u32 v0, v30, v0, s60
	s_waitcnt lgkmcnt(0)
	v_bfe_u32 v8, v32, 16, 1
	v_lshrrev_b32_e32 v0, 16, v0
	v_add3_u32 v8, v32, v8, s60
	v_and_or_b32 v19, v8, s85, v0
	v_or_b32_e32 v0, s5, v5
	v_lshlrev_b32_e32 v0, 11, v0
	v_lshl_add_u64 v[34:35], v[6:7], 0, v[0:1]
	v_bfe_u32 v0, v21, 16, 1
	v_add3_u32 v0, v21, v0, s60
	v_bfe_u32 v8, v9, 16, 1
	v_lshrrev_b32_e32 v0, 16, v0
	v_add3_u32 v8, v9, v8, s60
	global_store_dwordx4 v[34:35], v[16:19], off sc1
	s_nop 1
	v_and_or_b32 v16, v8, s85, v0
	v_bfe_u32 v0, v23, 16, 1
	v_add3_u32 v0, v23, v0, s60
	v_bfe_u32 v8, v25, 16, 1
	v_lshrrev_b32_e32 v0, 16, v0
	v_add3_u32 v8, v25, v8, s60
	v_and_or_b32 v17, v8, s85, v0
	v_bfe_u32 v0, v27, 16, 1
	v_add3_u32 v0, v27, v0, s60
	v_bfe_u32 v8, v29, 16, 1
	v_lshrrev_b32_e32 v0, 16, v0
	v_add3_u32 v8, v29, v8, s60
	v_and_or_b32 v18, v8, s85, v0
	v_bfe_u32 v0, v31, 16, 1
	v_add3_u32 v0, v31, v0, s60
	v_bfe_u32 v8, v33, 16, 1
	v_lshrrev_b32_e32 v0, 16, v0
	v_add3_u32 v8, v33, v8, s60
	v_and_or_b32 v19, v8, s85, v0
	v_or_b32_e32 v0, s5, v12
	v_lshlrev_b32_e32 v0, 11, v0
	v_lshl_add_u64 v[8:9], v[6:7], 0, v[0:1]
	global_store_dwordx4 v[8:9], v[16:19], off sc1
	ds_read2_b32 v[8:9], v15 offset0:49 offset1:57
	ds_read2_b32 v[20:21], v15 offset0:16 offset1:24
	ds_read2_b32 v[22:23], v15 offset0:82 offset1:90
	ds_read2_b32 v[24:25], v15 offset0:115 offset1:123
	ds_read2_b32 v[26:27], v15 offset0:148 offset1:156
	ds_read2_b32 v[28:29], v15 offset0:181 offset1:189
	ds_read2_b32 v[30:31], v15 offset0:214 offset1:222
	ds_read2_b32 v[32:33], v15 offset0:247 offset1:255
	s_waitcnt lgkmcnt(7)
	v_bfe_u32 v16, v8, 16, 1
	s_waitcnt lgkmcnt(6)
	v_bfe_u32 v0, v20, 16, 1
	v_add3_u32 v0, v20, v0, s60
	v_lshrrev_b32_e32 v0, 16, v0
	v_add3_u32 v8, v8, v16, s60
	v_and_or_b32 v16, v8, s85, v0
	s_waitcnt lgkmcnt(5)
	v_bfe_u32 v0, v22, 16, 1
	v_add3_u32 v0, v22, v0, s60
	s_waitcnt lgkmcnt(4)
	v_bfe_u32 v8, v24, 16, 1
	v_lshrrev_b32_e32 v0, 16, v0
	v_add3_u32 v8, v24, v8, s60
	v_and_or_b32 v17, v8, s85, v0
	s_waitcnt lgkmcnt(3)
	v_bfe_u32 v0, v26, 16, 1
	v_add3_u32 v0, v26, v0, s60
	s_waitcnt lgkmcnt(2)
	v_bfe_u32 v8, v28, 16, 1
	v_lshrrev_b32_e32 v0, 16, v0
	v_add3_u32 v8, v28, v8, s60
	v_and_or_b32 v18, v8, s85, v0
	s_waitcnt lgkmcnt(1)
	v_bfe_u32 v0, v30, 16, 1
	v_add3_u32 v0, v30, v0, s60
	s_waitcnt lgkmcnt(0)
	v_bfe_u32 v8, v32, 16, 1
	v_lshrrev_b32_e32 v0, 16, v0
	v_add3_u32 v8, v32, v8, s60
	v_and_or_b32 v19, v8, s85, v0
	v_or_b32_e32 v0, s5, v13
	v_lshlrev_b32_e32 v0, 11, v0
	v_lshl_add_u64 v[34:35], v[6:7], 0, v[0:1]
	v_bfe_u32 v0, v21, 16, 1
	v_add3_u32 v0, v21, v0, s60
	v_bfe_u32 v8, v9, 16, 1
	v_lshrrev_b32_e32 v0, 16, v0
	v_add3_u32 v8, v9, v8, s60
	global_store_dwordx4 v[34:35], v[16:19], off sc1
	s_nop 1
	v_and_or_b32 v16, v8, s85, v0
	v_bfe_u32 v0, v23, 16, 1
	v_add3_u32 v0, v23, v0, s60
	v_bfe_u32 v8, v25, 16, 1
	v_lshrrev_b32_e32 v0, 16, v0
	v_add3_u32 v8, v25, v8, s60
	v_and_or_b32 v17, v8, s85, v0
	v_bfe_u32 v0, v27, 16, 1
	v_add3_u32 v0, v27, v0, s60
	v_bfe_u32 v8, v29, 16, 1
	v_lshrrev_b32_e32 v0, 16, v0
	v_add3_u32 v8, v29, v8, s60
	v_and_or_b32 v18, v8, s85, v0
	v_bfe_u32 v0, v31, 16, 1
	v_add3_u32 v0, v31, v0, s60
	v_bfe_u32 v8, v33, 16, 1
	v_lshrrev_b32_e32 v0, 16, v0
	v_add3_u32 v8, v33, v8, s60
	v_and_or_b32 v19, v8, s85, v0
	v_or_b32_e32 v0, s5, v14
	v_lshlrev_b32_e32 v0, 11, v0
	v_lshl_add_u64 v[6:7], v[6:7], 0, v[0:1]
	global_store_dwordx4 v[6:7], v[16:19], off sc1
	s_waitcnt lgkmcnt(0)

.LBB0_421:
	s_andn2_b64 vcc, exec, s[6:7]
	s_cbranch_vccnz .LBB0_414
	s_mul_i32 s5, s16, 0xba3
	s_lshr_b32 s6, s5, 31
	s_ashr_i32 s5, s5, 22
	s_add_i32 s5, s5, s6
	s_mul_i32 s6, s5, 0x580
	s_sub_i32 s17, s16, s6
	v_add_u32_e32 v16, v10, v11
	s_mov_b64 s[6:7], -1
	s_cmpk_gt_i32 s16, 0x15ff
	s_sext_i32_i16 s16, s17
	v_lshlrev_b32_e32 v0, 2, v2
	v_add_u32_e32 v17, 0x420, v16
	v_add_u32_e32 v18, 0x428, v16
	v_add_u32_e32 v19, 0x840, v16
	v_add_u32_e32 v20, 0x848, v16
	v_add_u32_e32 v21, 0xc60, v16
	v_add_u32_e32 v22, 0xc68, v16
	v_add_u32_e32 v23, 0x1080, v16
	v_add_u32_e32 v24, 0x1088, v16
	v_add_u32_e32 v25, 0x14a0, v16
	v_add_u32_e32 v26, 0x14a8, v16
	v_add_u32_e32 v27, 0x18c0, v16
	v_add_u32_e32 v28, 0x18c8, v16
	v_add_u32_e32 v29, 0x1ce0, v16
	v_add_u32_e32 v30, 0x1ce8, v16
	v_lshlrev_b32_e32 v6, 1, v4
	s_cbranch_scc0 .LBB0_424
	s_load_dwordx2 s[6:7], s[8:9], 0x68
	s_lshl_b32 s18, s4, 1
	s_add_i32 s18, s18, s5
	s_add_i32 s18, s18, -4
	s_mul_i32 s20, s18, 0xb00000
	s_mul_hi_i32 s19, s18, 0xb00000
	s_waitcnt lgkmcnt(0)
	s_add_u32 s20, s6, s20
	s_addc_u32 s7, s7, s19
	s_mul_hi_i32 s6, s18, 0x580000
	s_mul_i32 s18, s18, 0x580000
	s_add_u32 s21, s12, s18
	s_addc_u32 s22, s13, s6
	s_lshl_b32 s6, s16, 1
	s_and_b32 s23, s6, 0xfc0
	s_lshl_b32 s6, s16, 5
	s_and_b32 s6, s6, 0x3e0
	s_lshl_b32 s18, s6, 2
	s_add_u32 s18, s20, s18
	v_or_b32_e32 v7, s23, v5
	s_addc_u32 s19, s7, 0
	v_lshl_add_u64 v[8:9], s[18:19], 0, v[0:1]
	v_lshlrev_b32_e32 v32, 12, v7
	v_mov_b32_e32 v33, v1
	v_lshl_add_u64 v[8:9], v[8:9], 0, v[32:33]
	s_mov_b32 s7, 0x8000
	global_load_dwordx4 v[32:35], v[8:9], off nt
	v_add_co_u32_e32 v36, vcc, s7, v8
	s_mov_b32 s7, 0x10000
	s_nop 0
	v_addc_co_u32_e32 v37, vcc, 0, v9, vcc
	global_load_dwordx4 v[36:39], v[36:37], off nt
	v_add_co_u32_e32 v40, vcc, s7, v8
	s_mov_b32 s7, 0x18000
	s_nop 0
	v_addc_co_u32_e32 v41, vcc, 0, v9, vcc
	global_load_dwordx4 v[40:43], v[40:41], off nt
	v_add_co_u32_e32 v44, vcc, s7, v8
	s_mov_b32 s7, 0x20000
	s_nop 0
	v_addc_co_u32_e32 v45, vcc, 0, v9, vcc
	global_load_dwordx4 v[44:47], v[44:45], off nt
	v_add_co_u32_e32 v48, vcc, s7, v8
	s_mov_b32 s7, 0x28000
	s_nop 0
	v_addc_co_u32_e32 v49, vcc, 0, v9, vcc
	global_load_dwordx4 v[48:51], v[48:49], off nt
	v_add_co_u32_e32 v52, vcc, s7, v8
	s_mov_b32 s7, 0x30000
	s_nop 0
	v_addc_co_u32_e32 v53, vcc, 0, v9, vcc
	global_load_dwordx4 v[52:55], v[52:53], off nt
	v_add_co_u32_e32 v56, vcc, s7, v8
	s_mov_b32 s7, 0x38000
	s_nop 0
	v_addc_co_u32_e32 v57, vcc, 0, v9, vcc
	global_load_dwordx4 v[56:59], v[56:57], off nt
	v_add_co_u32_e32 v8, vcc, s7, v8
	s_lshl_b32 s7, s23, 1
	s_nop 0
	v_addc_co_u32_e32 v9, vcc, 0, v9, vcc
	global_load_dwordx4 v[60:63], v[8:9], off nt
	s_add_u32 s18, s21, s7
	s_addc_u32 s19, s22, 0
	v_mov_b32_e32 v7, v1
	v_lshl_add_u64 v[8:9], s[18:19], 0, v[6:7]
	s_waitcnt vmcnt(0)
	ds_write2_b32 v16, v32, v33 offset1:1
	ds_write2_b32 v16, v34, v35 offset0:2 offset1:3
	ds_write2_b32 v17, v36, v37 offset1:1
	ds_write2_b32 v18, v38, v39 offset1:1
	ds_write2_b32 v19, v40, v41 offset1:1
	ds_write2_b32 v20, v42, v43 offset1:1
	ds_write2_b32 v21, v44, v45 offset1:1
	ds_write2_b32 v22, v46, v47 offset1:1
	ds_write2_b32 v23, v48, v49 offset1:1
	ds_write2_b32 v24, v50, v51 offset1:1
	ds_write2_b32 v25, v52, v53 offset1:1
	ds_write2_b32 v26, v54, v55 offset1:1
	ds_write2_b32 v27, v56, v57 offset1:1
	ds_write2_b32 v28, v58, v59 offset1:1
	ds_write2_b32 v29, v60, v61 offset1:1
	ds_write2_b32 v30, v62, v63 offset1:1
	s_waitcnt lgkmcnt(0)
	ds_read2_b32 v[36:37], v15 offset0:33 offset1:41
	ds_read2_b32 v[38:39], v15 offset1:8
	ds_read2_b32 v[40:41], v15 offset0:66 offset1:74
	ds_read2_b32 v[42:43], v15 offset0:99 offset1:107
	ds_read2_b32 v[44:45], v15 offset0:132 offset1:140
	ds_read2_b32 v[46:47], v15 offset0:165 offset1:173
	ds_read2_b32 v[48:49], v15 offset0:198 offset1:206
	ds_read2_b32 v[50:51], v15 offset0:231 offset1:239
	s_waitcnt lgkmcnt(7)
	v_bfe_u32 v31, v36, 16, 1
	s_waitcnt lgkmcnt(6)
	v_bfe_u32 v7, v38, 16, 1
	v_add3_u32 v7, v38, v7, s60
	v_lshrrev_b32_e32 v7, 16, v7
	v_add3_u32 v31, v36, v31, s60
	v_and_or_b32 v32, v31, s85, v7
	s_waitcnt lgkmcnt(5)
	v_bfe_u32 v7, v40, 16, 1
	v_add3_u32 v7, v40, v7, s60
	s_waitcnt lgkmcnt(4)
	v_bfe_u32 v31, v42, 16, 1
	v_lshrrev_b32_e32 v7, 16, v7
	v_add3_u32 v31, v42, v31, s60
	v_and_or_b32 v33, v31, s85, v7
	s_waitcnt lgkmcnt(3)
	v_bfe_u32 v7, v44, 16, 1
	v_add3_u32 v7, v44, v7, s60
	s_waitcnt lgkmcnt(2)
	v_bfe_u32 v31, v46, 16, 1
	v_lshrrev_b32_e32 v7, 16, v7
	v_add3_u32 v31, v46, v31, s60
	v_and_or_b32 v34, v31, s85, v7
	s_waitcnt lgkmcnt(1)
	v_bfe_u32 v7, v48, 16, 1
	v_add3_u32 v7, v48, v7, s60
	s_waitcnt lgkmcnt(0)
	v_bfe_u32 v31, v50, 16, 1
	v_lshrrev_b32_e32 v7, 16, v7
	v_add3_u32 v31, v50, v31, s60
	v_and_or_b32 v35, v31, s85, v7
	v_or_b32_e32 v7, s6, v5
	v_mul_u32_u24_e32 v7, 0xb00, v7
	v_lshlrev_b32_e32 v52, 1, v7
	v_bfe_u32 v7, v39, 16, 1
	v_mov_b32_e32 v53, v1
	v_add3_u32 v7, v39, v7, s60
	v_bfe_u32 v31, v37, 16, 1
	v_lshl_add_u64 v[52:53], v[8:9], 0, v[52:53]
	v_lshrrev_b32_e32 v7, 16, v7
	v_add3_u32 v31, v37, v31, s60
	global_store_dwordx4 v[52:53], v[32:35], off sc1
	v_mov_b32_e32 v37, v1
	v_mov_b32_e32 v53, v1
	v_and_or_b32 v32, v31, s85, v7
	v_bfe_u32 v7, v41, 16, 1
	v_add3_u32 v7, v41, v7, s60
	v_bfe_u32 v31, v43, 16, 1
	v_lshrrev_b32_e32 v7, 16, v7
	v_add3_u32 v31, v43, v31, s60
	v_and_or_b32 v33, v31, s85, v7
	v_bfe_u32 v7, v45, 16, 1
	v_add3_u32 v7, v45, v7, s60
	v_bfe_u32 v31, v47, 16, 1
	v_lshrrev_b32_e32 v7, 16, v7
	v_add3_u32 v31, v47, v31, s60
	v_and_or_b32 v34, v31, s85, v7
	v_bfe_u32 v7, v49, 16, 1
	v_add3_u32 v7, v49, v7, s60
	v_bfe_u32 v31, v51, 16, 1
	v_lshrrev_b32_e32 v7, 16, v7
	v_add3_u32 v31, v51, v31, s60
	v_and_or_b32 v35, v31, s85, v7
	v_or_b32_e32 v7, s6, v12
	v_mul_u32_u24_e32 v7, 0xb00, v7
	v_lshlrev_b32_e32 v36, 1, v7
	v_lshl_add_u64 v[36:37], v[8:9], 0, v[36:37]
	global_store_dwordx4 v[36:37], v[32:35], off sc1
	ds_read2_b32 v[36:37], v15 offset0:16 offset1:24
	ds_read2_b32 v[38:39], v15 offset0:49 offset1:57
	ds_read2_b32 v[40:41], v15 offset0:82 offset1:90
	ds_read2_b32 v[42:43], v15 offset0:115 offset1:123
	ds_read2_b32 v[44:45], v15 offset0:148 offset1:156
	ds_read2_b32 v[46:47], v15 offset0:181 offset1:189
	ds_read2_b32 v[48:49], v15 offset0:214 offset1:222
	ds_read2_b32 v[50:51], v15 offset0:247 offset1:255
	s_waitcnt lgkmcnt(7)
	v_bfe_u32 v7, v36, 16, 1
	v_add3_u32 v7, v36, v7, s60
	s_waitcnt lgkmcnt(6)
	v_bfe_u32 v31, v38, 16, 1
	v_lshrrev_b32_e32 v7, 16, v7
	v_add3_u32 v31, v38, v31, s60
	v_and_or_b32 v32, v31, s85, v7
	s_waitcnt lgkmcnt(5)
	v_bfe_u32 v7, v40, 16, 1
	v_add3_u32 v7, v40, v7, s60
	s_waitcnt lgkmcnt(4)
	v_bfe_u32 v31, v42, 16, 1
	v_lshrrev_b32_e32 v7, 16, v7
	v_add3_u32 v31, v42, v31, s60
	v_and_or_b32 v33, v31, s85, v7
	s_waitcnt lgkmcnt(3)
	v_bfe_u32 v7, v44, 16, 1
	v_add3_u32 v7, v44, v7, s60
	s_waitcnt lgkmcnt(2)
	v_bfe_u32 v31, v46, 16, 1
	v_lshrrev_b32_e32 v7, 16, v7
	v_add3_u32 v31, v46, v31, s60
	v_and_or_b32 v34, v31, s85, v7
	s_waitcnt lgkmcnt(1)
	v_bfe_u32 v7, v48, 16, 1
	v_add3_u32 v7, v48, v7, s60
	s_waitcnt lgkmcnt(0)
	v_bfe_u32 v31, v50, 16, 1
	v_lshrrev_b32_e32 v7, 16, v7
	v_add3_u32 v31, v50, v31, s60
	v_and_or_b32 v35, v31, s85, v7
	v_or_b32_e32 v7, s6, v13
	v_mul_u32_u24_e32 v7, 0xb00, v7
	v_lshlrev_b32_e32 v52, 1, v7
	v_bfe_u32 v7, v37, 16, 1
	v_add3_u32 v7, v37, v7, s60
	v_bfe_u32 v31, v39, 16, 1
	v_lshl_add_u64 v[52:53], v[8:9], 0, v[52:53]
	v_lshrrev_b32_e32 v7, 16, v7
	v_add3_u32 v31, v39, v31, s60
	global_store_dwordx4 v[52:53], v[32:35], off sc1
	v_mov_b32_e32 v37, v1
	s_nop 0
	v_and_or_b32 v32, v31, s85, v7
	v_bfe_u32 v7, v41, 16, 1
	v_add3_u32 v7, v41, v7, s60
	v_bfe_u32 v31, v43, 16, 1
	v_lshrrev_b32_e32 v7, 16, v7
	v_add3_u32 v31, v43, v31, s60
	v_and_or_b32 v33, v31, s85, v7
	v_bfe_u32 v7, v45, 16, 1
	v_add3_u32 v7, v45, v7, s60
	v_bfe_u32 v31, v47, 16, 1
	v_lshrrev_b32_e32 v7, 16, v7
	v_add3_u32 v31, v47, v31, s60
	v_and_or_b32 v34, v31, s85, v7
	v_bfe_u32 v7, v49, 16, 1
	v_add3_u32 v7, v49, v7, s60
	v_bfe_u32 v31, v51, 16, 1
	v_lshrrev_b32_e32 v7, 16, v7
	v_add3_u32 v31, v51, v31, s60
	v_and_or_b32 v35, v31, s85, v7
	v_or_b32_e32 v7, s6, v14
	v_mul_u32_u24_e32 v7, 0xb00, v7
	v_lshlrev_b32_e32 v36, 1, v7
	v_lshl_add_u64 v[8:9], v[8:9], 0, v[36:37]
	global_store_dwordx4 v[8:9], v[32:35], off sc1
	s_waitcnt lgkmcnt(0)
	s_mov_b64 s[6:7], 0
.LBB0_424:
	s_andn2_b64 vcc, exec, s[6:7]
	s_cbranch_vccnz .LBB0_414
	s_and_b32 s18, s5, 1
	s_and_b32 s6, s5, 0xffff
	s_cmp_lt_u32 s6, 2
	s_movk_i32 s6, 0x60
	s_cselect_b32 s6, 0x58, s6
	s_add_u32 s6, s8, s6
	s_addc_u32 s7, s9, 0
	s_load_dwordx2 s[6:7], s[6:7], 0x0
	s_lshl_b32 s4, s4, 1
	s_or_b32 s4, s18, s4
	s_mul_i32 s19, s4, 0xb00000
	s_mul_hi_i32 s18, s4, 0xb00000
	s_waitcnt lgkmcnt(0)
	s_add_u32 s20, s6, s19
	s_mulk_i32 s16, 0xba3
	s_addc_u32 s7, s7, s18
	s_lshr_b32 s4, s16, 31
	s_ashr_i32 s6, s16, 18
	s_add_i32 s4, s6, s4
	s_sext_i32_i16 s6, s4
	s_mulk_i32 s4, 0x58
	s_sub_i32 s4, s17, s4
	s_sext_i32_i16 s17, s4
	s_lshl_b32 s4, s17, 5
	s_add_u32 s19, s10, s19
	s_addc_u32 s18, s11, s18
	s_lshl_b32 s16, s6, 6
	s_lshl_b32 s6, s17, 6
	s_lshl_b32 s5, s5, 6
	s_and_b32 s6, s6, 0xffffff00
	s_and_b32 s5, s5, 0xffffff80
	s_add_i32 s6, s6, s5
	s_and_b32 s5, s4, 0x60
	s_or_b32 s6, s6, s5
	s_ashr_i32 s5, s4, 31
	s_lshl_b64 s[4:5], s[4:5], 2
	v_or_b32_e32 v7, s16, v5
	s_add_u32 s4, s20, s4
	s_addc_u32 s5, s7, s5
	v_mul_i32_i24_e32 v32, 0xb00, v7
	v_lshl_add_u64 v[8:9], s[4:5], 0, v[0:1]
	v_ashrrev_i32_e32 v33, 31, v32
	v_lshl_add_u64 v[8:9], v[32:33], 2, v[8:9]
	s_mov_b32 s4, 0x16000
	global_load_dwordx4 v[32:35], v[8:9], off nt
	v_add_co_u32_e32 v36, vcc, s4, v8
	s_mov_b32 s4, 0x2c000
	s_nop 0
	v_addc_co_u32_e32 v37, vcc, 0, v9, vcc
	global_load_dwordx4 v[36:39], v[36:37], off nt
	v_add_co_u32_e32 v40, vcc, s4, v8
	s_mov_b32 s4, 0x42000
	s_nop 0
	v_addc_co_u32_e32 v41, vcc, 0, v9, vcc
	global_load_dwordx4 v[40:43], v[40:41], off nt
	v_add_co_u32_e32 v44, vcc, s4, v8
	s_mov_b32 s4, 0x58000
	s_nop 0
	v_addc_co_u32_e32 v45, vcc, 0, v9, vcc
	global_load_dwordx4 v[44:47], v[44:45], off nt
	v_add_co_u32_e32 v48, vcc, s4, v8
	s_mov_b32 s4, 0x6e000
	s_nop 0
	v_addc_co_u32_e32 v49, vcc, 0, v9, vcc
	global_load_dwordx4 v[48:51], v[48:49], off nt
	v_add_co_u32_e32 v52, vcc, s4, v8
	s_mov_b32 s4, 0x84000
	s_nop 0
	v_addc_co_u32_e32 v53, vcc, 0, v9, vcc
	global_load_dwordx4 v[52:55], v[52:53], off nt
	v_add_co_u32_e32 v56, vcc, s4, v8
	s_mov_b32 s4, 0x9a000
	s_nop 0
	v_addc_co_u32_e32 v57, vcc, 0, v9, vcc
	global_load_dwordx4 v[56:59], v[56:57], off nt
	v_add_co_u32_e32 v8, vcc, s4, v8
	s_ashr_i32 s17, s16, 31
	s_nop 0
	v_addc_co_u32_e32 v9, vcc, 0, v9, vcc
	global_load_dwordx4 v[60:63], v[8:9], off nt
	s_lshl_b64 s[4:5], s[16:17], 1
	s_add_u32 s4, s19, s4
	s_addc_u32 s5, s18, s5
	v_mov_b32_e32 v7, v1
	v_lshl_add_u64 v[6:7], s[4:5], 0, v[6:7]
	s_waitcnt vmcnt(0)
	ds_write2_b32 v16, v32, v33 offset1:1
	ds_write2_b32 v16, v34, v35 offset0:2 offset1:3
	ds_write2_b32 v17, v36, v37 offset1:1
	ds_write2_b32 v18, v38, v39 offset1:1
	ds_write2_b32 v19, v40, v41 offset1:1
	ds_write2_b32 v20, v42, v43 offset1:1
	ds_write2_b32 v21, v44, v45 offset1:1
	ds_write2_b32 v22, v46, v47 offset1:1
	ds_write2_b32 v23, v48, v49 offset1:1
	ds_write2_b32 v24, v50, v51 offset1:1
	ds_write2_b32 v25, v52, v53 offset1:1
	ds_write2_b32 v26, v54, v55 offset1:1
	ds_write2_b32 v27, v56, v57 offset1:1
	ds_write2_b32 v28, v58, v59 offset1:1
	ds_write2_b32 v29, v60, v61 offset1:1
	ds_write2_b32 v30, v62, v63 offset1:1
	s_waitcnt lgkmcnt(0)
	ds_read2_b32 v[8:9], v15 offset0:33 offset1:41
	ds_read2_b32 v[20:21], v15 offset1:8
	ds_read2_b32 v[22:23], v15 offset0:66 offset1:74
	ds_read2_b32 v[24:25], v15 offset0:99 offset1:107
	ds_read2_b32 v[26:27], v15 offset0:132 offset1:140
	ds_read2_b32 v[28:29], v15 offset0:165 offset1:173
	ds_read2_b32 v[30:31], v15 offset0:198 offset1:206
	ds_read2_b32 v[32:33], v15 offset0:231 offset1:239
	s_waitcnt lgkmcnt(7)
	v_bfe_u32 v16, v8, 16, 1
	s_waitcnt lgkmcnt(6)
	v_bfe_u32 v0, v20, 16, 1
	v_add3_u32 v0, v20, v0, s60
	v_lshrrev_b32_e32 v0, 16, v0
	v_add3_u32 v8, v8, v16, s60
	v_and_or_b32 v16, v8, s85, v0
	s_waitcnt lgkmcnt(5)
	v_bfe_u32 v0, v22, 16, 1
	v_add3_u32 v0, v22, v0, s60
	s_waitcnt lgkmcnt(4)
	v_bfe_u32 v8, v24, 16, 1
	v_lshrrev_b32_e32 v0, 16, v0
	v_add3_u32 v8, v24, v8, s60
	v_and_or_b32 v17, v8, s85, v0
	s_waitcnt lgkmcnt(3)
	v_bfe_u32 v0, v26, 16, 1
	v_add3_u32 v0, v26, v0, s60
	s_waitcnt lgkmcnt(2)
	v_bfe_u32 v8, v28, 16, 1
	v_lshrrev_b32_e32 v0, 16, v0
	v_add3_u32 v8, v28, v8, s60
	v_and_or_b32 v18, v8, s85, v0
	s_waitcnt lgkmcnt(1)
	v_bfe_u32 v0, v30, 16, 1
	v_add3_u32 v0, v30, v0, s60
	s_waitcnt lgkmcnt(0)
	v_bfe_u32 v8, v32, 16, 1
	v_lshrrev_b32_e32 v0, 16, v0
	v_add3_u32 v8, v32, v8, s60
	v_or_b32_e32 v34, s6, v5
	v_and_or_b32 v19, v8, s85, v0
	v_ashrrev_i32_e32 v35, 31, v34
	v_bfe_u32 v0, v21, 16, 1
	v_lshlrev_b64 v[34:35], 11, v[34:35]
	v_add3_u32 v0, v21, v0, s60
	v_bfe_u32 v8, v9, 16, 1
	v_lshl_add_u64 v[34:35], v[6:7], 0, v[34:35]
	v_lshrrev_b32_e32 v0, 16, v0
	v_add3_u32 v8, v9, v8, s60
	global_store_dwordx4 v[34:35], v[16:19], off sc1
	v_or_b32_e32 v34, s6, v13
	v_ashrrev_i32_e32 v35, 31, v34
	v_and_or_b32 v16, v8, s85, v0
	v_bfe_u32 v0, v23, 16, 1
	v_add3_u32 v0, v23, v0, s60
	v_bfe_u32 v8, v25, 16, 1
	v_lshrrev_b32_e32 v0, 16, v0
	v_add3_u32 v8, v25, v8, s60
	v_and_or_b32 v17, v8, s85, v0
	v_bfe_u32 v0, v27, 16, 1
	v_add3_u32 v0, v27, v0, s60
	v_bfe_u32 v8, v29, 16, 1
	v_lshrrev_b32_e32 v0, 16, v0
	v_add3_u32 v8, v29, v8, s60
	v_and_or_b32 v18, v8, s85, v0
	v_bfe_u32 v0, v31, 16, 1
	v_add3_u32 v0, v31, v0, s60
	v_bfe_u32 v8, v33, 16, 1
	v_lshrrev_b32_e32 v0, 16, v0
	v_add3_u32 v8, v33, v8, s60
	v_and_or_b32 v19, v8, s85, v0
	v_or_b32_e32 v8, s6, v12
	v_ashrrev_i32_e32 v9, 31, v8
	v_lshlrev_b64 v[8:9], 11, v[8:9]
	v_lshl_add_u64 v[8:9], v[6:7], 0, v[8:9]
	global_store_dwordx4 v[8:9], v[16:19], off sc1
	ds_read2_b32 v[8:9], v15 offset0:49 offset1:57
	ds_read2_b32 v[20:21], v15 offset0:16 offset1:24
	ds_read2_b32 v[22:23], v15 offset0:82 offset1:90
	ds_read2_b32 v[24:25], v15 offset0:115 offset1:123
	ds_read2_b32 v[26:27], v15 offset0:148 offset1:156
	ds_read2_b32 v[28:29], v15 offset0:181 offset1:189
	ds_read2_b32 v[30:31], v15 offset0:214 offset1:222
	ds_read2_b32 v[32:33], v15 offset0:247 offset1:255
	s_waitcnt lgkmcnt(7)
	v_bfe_u32 v16, v8, 16, 1
	s_waitcnt lgkmcnt(6)
	v_bfe_u32 v0, v20, 16, 1
	v_add3_u32 v0, v20, v0, s60
	v_lshrrev_b32_e32 v0, 16, v0
	v_add3_u32 v8, v8, v16, s60
	v_and_or_b32 v16, v8, s85, v0
	s_waitcnt lgkmcnt(5)
	v_bfe_u32 v0, v22, 16, 1
	v_add3_u32 v0, v22, v0, s60
	s_waitcnt lgkmcnt(4)
	v_bfe_u32 v8, v24, 16, 1
	v_lshrrev_b32_e32 v0, 16, v0
	v_add3_u32 v8, v24, v8, s60
	v_and_or_b32 v17, v8, s85, v0
	s_waitcnt lgkmcnt(3)
	v_bfe_u32 v0, v26, 16, 1
	v_add3_u32 v0, v26, v0, s60
	s_waitcnt lgkmcnt(2)
	v_bfe_u32 v8, v28, 16, 1
	v_lshrrev_b32_e32 v0, 16, v0
	v_add3_u32 v8, v28, v8, s60
	v_and_or_b32 v18, v8, s85, v0
	s_waitcnt lgkmcnt(1)
	v_bfe_u32 v0, v30, 16, 1
	v_add3_u32 v0, v30, v0, s60
	s_waitcnt lgkmcnt(0)
	v_bfe_u32 v8, v32, 16, 1
	v_lshrrev_b32_e32 v0, 16, v0
	v_add3_u32 v8, v32, v8, s60
	v_and_or_b32 v19, v8, s85, v0
	v_bfe_u32 v0, v21, 16, 1
	v_lshlrev_b64 v[34:35], 11, v[34:35]
	v_add3_u32 v0, v21, v0, s60
	v_bfe_u32 v8, v9, 16, 1
	v_lshl_add_u64 v[34:35], v[6:7], 0, v[34:35]
	v_lshrrev_b32_e32 v0, 16, v0
	v_add3_u32 v8, v9, v8, s60
	global_store_dwordx4 v[34:35], v[16:19], off sc1
	s_nop 1
	v_and_or_b32 v16, v8, s85, v0
	v_bfe_u32 v0, v23, 16, 1
	v_add3_u32 v0, v23, v0, s60
	v_bfe_u32 v8, v25, 16, 1
	v_lshrrev_b32_e32 v0, 16, v0
	v_add3_u32 v8, v25, v8, s60
	v_and_or_b32 v17, v8, s85, v0
	v_bfe_u32 v0, v27, 16, 1
	v_add3_u32 v0, v27, v0, s60
	v_bfe_u32 v8, v29, 16, 1
	v_lshrrev_b32_e32 v0, 16, v0
	v_add3_u32 v8, v29, v8, s60
	v_and_or_b32 v18, v8, s85, v0
	v_bfe_u32 v0, v31, 16, 1
	v_add3_u32 v0, v31, v0, s60
	v_bfe_u32 v8, v33, 16, 1
	v_lshrrev_b32_e32 v0, 16, v0
	v_add3_u32 v8, v33, v8, s60
	v_and_or_b32 v19, v8, s85, v0
	v_or_b32_e32 v8, s6, v14
	v_ashrrev_i32_e32 v9, 31, v8
	v_lshlrev_b64 v[8:9], 11, v[8:9]
	v_lshl_add_u64 v[6:7], v[6:7], 0, v[8:9]
	global_store_dwordx4 v[6:7], v[16:19], off sc1
	s_waitcnt lgkmcnt(0)
	s_branch .LBB0_414

.LBB0_432:
	v_readlane_b32 s4, v255, 19
	s_add_i32 s4, s4, s15
	s_add_i32 s5, s4, 0x1d80
	s_mul_hi_i32 s4, s5, 0x66666667
	s_lshr_b32 s6, s4, 31
	s_ashr_i32 s4, s4, 12
	s_add_i32 s4, s4, s6
	s_mul_i32 s6, s4, 0x2800
	s_sub_i32 s16, s5, s6
	s_cmpk_gt_i32 s16, 0x20ff
	s_mov_b64 s[6:7], -1
	s_cbranch_scc0 .LBB0_438
	s_cmpk_gt_u32 s16, 0x25ff
	s_cbranch_scc0 .LBB0_435
	s_load_dwordx2 s[6:7], s[8:9], 0x78
	s_ashr_i32 s5, s4, 31
	s_lshl_b64 s[18:19], s[4:5], 22
	v_lshlrev_b32_e32 v0, 2, v2
	v_mov_b32_e32 v41, v1
	s_waitcnt lgkmcnt(0)
	s_add_u32 s17, s6, s18
	s_addc_u32 s18, s7, s19
	s_lshl_b64 s[6:7], s[4:5], 21
	s_add_u32 s19, s0, s6
	s_addc_u32 s20, s1, s7
	s_lshl_b32 s5, s16, 1
	s_and_b32 s5, s5, 0x7fffffc0
	s_add_i32 s44, s5, 0xffffb400
	s_lshl_b32 s5, s16, 5
	s_and_b32 s5, s5, 0x3e0
	s_lshl_b32 s6, s5, 2
	s_add_u32 s6, s17, s6
	v_or_b32_e32 v40, s44, v5
	s_addc_u32 s7, s18, 0
	v_lshl_add_u64 v[42:43], s[6:7], 0, v[0:1]
	v_lshlrev_b64 v[6:7], 12, v[40:41]
	v_or_b32_e32 v0, 8, v40
	v_lshl_add_u64 v[6:7], v[42:43], 0, v[6:7]
	v_lshlrev_b64 v[16:17], 12, v[0:1]
	global_load_dwordx4 v[6:9], v[6:7], off nt
	v_lshl_add_u64 v[16:17], v[42:43], 0, v[16:17]
	v_or_b32_e32 v0, 16, v40
	global_load_dwordx4 v[16:19], v[16:17], off nt
	v_lshlrev_b64 v[20:21], 12, v[0:1]
	v_lshl_add_u64 v[20:21], v[42:43], 0, v[20:21]
	v_or_b32_e32 v0, 24, v40
	global_load_dwordx4 v[20:23], v[20:21], off nt
	v_lshlrev_b64 v[24:25], 12, v[0:1]
	v_lshl_add_u64 v[24:25], v[42:43], 0, v[24:25]
	v_or_b32_e32 v0, 32, v40
	global_load_dwordx4 v[24:27], v[24:25], off nt
	v_lshlrev_b64 v[28:29], 12, v[0:1]
	v_lshl_add_u64 v[28:29], v[42:43], 0, v[28:29]
	v_or_b32_e32 v0, 40, v40
	global_load_dwordx4 v[28:31], v[28:29], off nt
	v_lshlrev_b64 v[32:33], 12, v[0:1]
	v_lshl_add_u64 v[32:33], v[42:43], 0, v[32:33]
	v_or_b32_e32 v0, 48, v40
	global_load_dwordx4 v[32:35], v[32:33], off nt
	v_lshlrev_b64 v[36:37], 12, v[0:1]
	v_lshl_add_u64 v[36:37], v[42:43], 0, v[36:37]
	v_or_b32_e32 v0, 56, v40
	global_load_dwordx4 v[36:39], v[36:37], off nt
	v_lshlrev_b64 v[40:41], 12, v[0:1]
	v_lshl_add_u64 v[40:41], v[42:43], 0, v[40:41]
	global_load_dwordx4 v[40:43], v[40:41], off nt
	v_add_u32_e32 v0, v10, v11
	s_lshl_b64 s[6:7], s[44:45], 1
	s_add_u32 s6, s19, s6
	s_addc_u32 s7, s20, s7
	s_waitcnt vmcnt(0)
	ds_write2_b32 v0, v6, v7 offset1:1
	ds_write2_b32 v0, v8, v9 offset0:2 offset1:3
	v_add_u32_e32 v6, 0x420, v0
	ds_write2_b32 v6, v16, v17 offset1:1
	v_add_u32_e32 v6, 0x428, v0
	ds_write2_b32 v6, v18, v19 offset1:1
	v_add_u32_e32 v6, 0x840, v0
	ds_write2_b32 v6, v20, v21 offset1:1
	v_add_u32_e32 v6, 0x848, v0
	ds_write2_b32 v6, v22, v23 offset1:1
	v_add_u32_e32 v6, 0xc60, v0
	ds_write2_b32 v6, v24, v25 offset1:1
	v_add_u32_e32 v6, 0xc68, v0
	ds_write2_b32 v6, v26, v27 offset1:1
	v_add_u32_e32 v6, 0x1080, v0
	ds_write2_b32 v6, v28, v29 offset1:1
	v_add_u32_e32 v6, 0x1088, v0
	ds_write2_b32 v6, v30, v31 offset1:1
	v_add_u32_e32 v6, 0x14a0, v0
	ds_write2_b32 v6, v32, v33 offset1:1
	v_add_u32_e32 v6, 0x14a8, v0
	ds_write2_b32 v6, v34, v35 offset1:1
	v_add_u32_e32 v6, 0x18c0, v0
	ds_write2_b32 v6, v36, v37 offset1:1
	v_add_u32_e32 v6, 0x18c8, v0
	ds_write2_b32 v6, v38, v39 offset1:1
	v_add_u32_e32 v6, 0x1ce0, v0
	v_add_u32_e32 v0, 0x1ce8, v0
	ds_write2_b32 v6, v40, v41 offset1:1
	ds_write2_b32 v0, v42, v43 offset1:1
	s_waitcnt lgkmcnt(0)
	ds_read2_b32 v[8:9], v15 offset0:33 offset1:41
	ds_read2_b32 v[20:21], v15 offset1:8
	v_lshlrev_b32_e32 v0, 1, v4
	ds_read2_b32 v[22:23], v15 offset0:66 offset1:74
	ds_read2_b32 v[24:25], v15 offset0:99 offset1:107
	v_lshl_add_u64 v[6:7], s[6:7], 0, v[0:1]
	s_waitcnt lgkmcnt(3)
	v_bfe_u32 v16, v8, 16, 1
	s_waitcnt lgkmcnt(2)
	v_bfe_u32 v0, v20, 16, 1
	v_add3_u32 v0, v20, v0, s60
	v_lshrrev_b32_e32 v0, 16, v0
	v_add3_u32 v8, v8, v16, s60
	ds_read2_b32 v[26:27], v15 offset0:132 offset1:140
	ds_read2_b32 v[28:29], v15 offset0:165 offset1:173
	v_and_or_b32 v16, v8, s85, v0
	s_waitcnt lgkmcnt(3)
	v_bfe_u32 v0, v22, 16, 1
	v_add3_u32 v0, v22, v0, s60
	s_waitcnt lgkmcnt(2)
	v_bfe_u32 v8, v24, 16, 1
	v_lshrrev_b32_e32 v0, 16, v0
	v_add3_u32 v8, v24, v8, s60
	ds_read2_b32 v[30:31], v15 offset0:198 offset1:206
	ds_read2_b32 v[32:33], v15 offset0:231 offset1:239
	v_and_or_b32 v17, v8, s85, v0
	s_waitcnt lgkmcnt(3)
	v_bfe_u32 v0, v26, 16, 1
	v_add3_u32 v0, v26, v0, s60
	s_waitcnt lgkmcnt(2)
	v_bfe_u32 v8, v28, 16, 1
	v_lshrrev_b32_e32 v0, 16, v0
	v_add3_u32 v8, v28, v8, s60
	v_and_or_b32 v18, v8, s85, v0
	s_waitcnt lgkmcnt(1)
	v_bfe_u32 v0, v30, 16, 1
	v_add3_u32 v0, v30, v0, s60
	s_waitcnt lgkmcnt(0)
	v_bfe_u32 v8, v32, 16, 1
	v_lshrrev_b32_e32 v0, 16, v0
	v_add3_u32 v8, v32, v8, s60
	v_and_or_b32 v19, v8, s85, v0
	v_or_b32_e32 v0, s5, v5
	v_lshlrev_b32_e32 v0, 11, v0
	v_lshl_add_u64 v[34:35], v[6:7], 0, v[0:1]
	v_bfe_u32 v0, v21, 16, 1
	v_add3_u32 v0, v21, v0, s60
	v_bfe_u32 v8, v9, 16, 1
	v_lshrrev_b32_e32 v0, 16, v0
	v_add3_u32 v8, v9, v8, s60
	global_store_dwordx4 v[34:35], v[16:19], off sc1
	s_mov_b64 s[6:7], 0
	s_nop 0
	v_and_or_b32 v16, v8, s85, v0
	v_bfe_u32 v0, v23, 16, 1
	v_add3_u32 v0, v23, v0, s60
	v_bfe_u32 v8, v25, 16, 1
	v_lshrrev_b32_e32 v0, 16, v0
	v_add3_u32 v8, v25, v8, s60
	v_and_or_b32 v17, v8, s85, v0
	v_bfe_u32 v0, v27, 16, 1
	v_add3_u32 v0, v27, v0, s60
	v_bfe_u32 v8, v29, 16, 1
	v_lshrrev_b32_e32 v0, 16, v0
	v_add3_u32 v8, v29, v8, s60
	v_and_or_b32 v18, v8, s85, v0
	v_bfe_u32 v0, v31, 16, 1
	v_add3_u32 v0, v31, v0, s60
	v_bfe_u32 v8, v33, 16, 1
	v_lshrrev_b32_e32 v0, 16, v0
	v_add3_u32 v8, v33, v8, s60
	v_and_or_b32 v19, v8, s85, v0
	v_or_b32_e32 v0, s5, v12
	v_lshlrev_b32_e32 v0, 11, v0
	v_lshl_add_u64 v[8:9], v[6:7], 0, v[0:1]
	global_store_dwordx4 v[8:9], v[16:19], off sc1
	ds_read2_b32 v[8:9], v15 offset0:49 offset1:57
	ds_read2_b32 v[20:21], v15 offset0:16 offset1:24
	ds_read2_b32 v[22:23], v15 offset0:82 offset1:90
	ds_read2_b32 v[24:25], v15 offset0:115 offset1:123
	ds_read2_b32 v[26:27], v15 offset0:148 offset1:156
	ds_read2_b32 v[28:29], v15 offset0:181 offset1:189
	ds_read2_b32 v[30:31], v15 offset0:214 offset1:222
	ds_read2_b32 v[32:33], v15 offset0:247 offset1:255
	s_waitcnt lgkmcnt(7)
	v_bfe_u32 v16, v8, 16, 1
	s_waitcnt lgkmcnt(6)
	v_bfe_u32 v0, v20, 16, 1
	v_add3_u32 v0, v20, v0, s60
	v_lshrrev_b32_e32 v0, 16, v0
	v_add3_u32 v8, v8, v16, s60
	v_and_or_b32 v16, v8, s85, v0
	s_waitcnt lgkmcnt(5)
	v_bfe_u32 v0, v22, 16, 1
	v_add3_u32 v0, v22, v0, s60
	s_waitcnt lgkmcnt(4)
	v_bfe_u32 v8, v24, 16, 1
	v_lshrrev_b32_e32 v0, 16, v0
	v_add3_u32 v8, v24, v8, s60
	v_and_or_b32 v17, v8, s85, v0
	s_waitcnt lgkmcnt(3)
	v_bfe_u32 v0, v26, 16, 1
	v_add3_u32 v0, v26, v0, s60
	s_waitcnt lgkmcnt(2)
	v_bfe_u32 v8, v28, 16, 1
	v_lshrrev_b32_e32 v0, 16, v0
	v_add3_u32 v8, v28, v8, s60
	v_and_or_b32 v18, v8, s85, v0
	s_waitcnt lgkmcnt(1)
	v_bfe_u32 v0, v30, 16, 1
	v_add3_u32 v0, v30, v0, s60
	s_waitcnt lgkmcnt(0)
	v_bfe_u32 v8, v32, 16, 1
	v_lshrrev_b32_e32 v0, 16, v0
	v_add3_u32 v8, v32, v8, s60
	v_and_or_b32 v19, v8, s85, v0
	v_or_b32_e32 v0, s5, v13
	v_lshlrev_b32_e32 v0, 11, v0
	v_lshl_add_u64 v[34:35], v[6:7], 0, v[0:1]
	v_bfe_u32 v0, v21, 16, 1
	v_add3_u32 v0, v21, v0, s60
	v_bfe_u32 v8, v9, 16, 1
	v_lshrrev_b32_e32 v0, 16, v0
	v_add3_u32 v8, v9, v8, s60
	global_store_dwordx4 v[34:35], v[16:19], off sc1
	s_nop 1
	v_and_or_b32 v16, v8, s85, v0
	v_bfe_u32 v0, v23, 16, 1
	v_add3_u32 v0, v23, v0, s60
	v_bfe_u32 v8, v25, 16, 1
	v_lshrrev_b32_e32 v0, 16, v0
	v_add3_u32 v8, v25, v8, s60
	v_and_or_b32 v17, v8, s85, v0
	v_bfe_u32 v0, v27, 16, 1
	v_add3_u32 v0, v27, v0, s60
	v_bfe_u32 v8, v29, 16, 1
	v_lshrrev_b32_e32 v0, 16, v0
	v_add3_u32 v8, v29, v8, s60
	v_and_or_b32 v18, v8, s85, v0
	v_bfe_u32 v0, v31, 16, 1
	v_add3_u32 v0, v31, v0, s60
	v_bfe_u32 v8, v33, 16, 1
	v_lshrrev_b32_e32 v0, 16, v0
	v_add3_u32 v8, v33, v8, s60
	v_and_or_b32 v19, v8, s85, v0
	v_or_b32_e32 v0, s5, v14
	v_lshlrev_b32_e32 v0, 11, v0
	v_lshl_add_u64 v[6:7], v[6:7], 0, v[0:1]
	global_store_dwordx4 v[6:7], v[16:19], off sc1
	s_waitcnt lgkmcnt(0)

.LBB0_448:
	s_addk_i32 s14, 0x200
	s_cmpk_lt_u32 s14, 0xb00
	s_movk_i32 s4, 0x2280
	s_cselect_b32 s4, s4, 0x2800
	s_cmpk_gt_i32 s14, 0x57f
	s_cselect_b32 s4, s4, 0x1b80
	s_add_i32 s5, s14, s4
	s_mul_hi_i32 s4, s5, 0x66666667
	s_lshr_b32 s6, s4, 31
	s_ashr_i32 s4, s4, 12
	s_add_i32 s4, s4, s6
	s_mul_i32 s6, s4, 0x2800
	s_sub_i32 s15, s5, s6
	s_cmpk_gt_i32 s15, 0x20ff
	s_mov_b64 s[6:7], -1
	s_cbranch_scc0 .LBB0_454
	s_cmpk_gt_u32 s15, 0x25ff
	s_cbranch_scc0 .LBB0_451
	s_load_dwordx2 s[6:7], s[8:9], 0x78
	s_ashr_i32 s5, s4, 31
	s_lshl_b64 s[16:17], s[4:5], 22
	v_lshlrev_b32_e32 v0, 2, v2
	v_mov_b32_e32 v41, v1
	s_waitcnt lgkmcnt(0)
	s_add_u32 s16, s6, s16
	s_addc_u32 s17, s7, s17
	s_lshl_b64 s[6:7], s[4:5], 21
	s_add_u32 s18, s0, s6
	s_addc_u32 s19, s1, s7
	s_lshl_b32 s5, s15, 1
	s_and_b32 s5, s5, 0x7fffffc0
	s_add_i32 s44, s5, 0xffffb400
	s_lshl_b32 s5, s15, 5
	s_and_b32 s5, s5, 0x3e0
	s_lshl_b32 s6, s5, 2
	s_add_u32 s6, s16, s6
	v_or_b32_e32 v40, s44, v3
	s_addc_u32 s7, s17, 0
	v_lshl_add_u64 v[42:43], s[6:7], 0, v[0:1]
	v_lshlrev_b64 v[6:7], 12, v[40:41]
	v_or_b32_e32 v0, 8, v40
	v_lshl_add_u64 v[6:7], v[42:43], 0, v[6:7]
	v_lshlrev_b64 v[16:17], 12, v[0:1]
	global_load_dwordx4 v[6:9], v[6:7], off nt
	v_lshl_add_u64 v[16:17], v[42:43], 0, v[16:17]
	v_or_b32_e32 v0, 16, v40
	global_load_dwordx4 v[16:19], v[16:17], off nt
	v_lshlrev_b64 v[20:21], 12, v[0:1]
	v_lshl_add_u64 v[20:21], v[42:43], 0, v[20:21]
	v_or_b32_e32 v0, 24, v40
	global_load_dwordx4 v[20:23], v[20:21], off nt
	v_lshlrev_b64 v[24:25], 12, v[0:1]
	v_lshl_add_u64 v[24:25], v[42:43], 0, v[24:25]
	v_or_b32_e32 v0, 32, v40
	global_load_dwordx4 v[24:27], v[24:25], off nt
	v_lshlrev_b64 v[28:29], 12, v[0:1]
	v_lshl_add_u64 v[28:29], v[42:43], 0, v[28:29]
	v_or_b32_e32 v0, 40, v40
	global_load_dwordx4 v[28:31], v[28:29], off nt
	v_lshlrev_b64 v[32:33], 12, v[0:1]
	v_lshl_add_u64 v[32:33], v[42:43], 0, v[32:33]
	v_or_b32_e32 v0, 48, v40
	global_load_dwordx4 v[32:35], v[32:33], off nt
	v_lshlrev_b64 v[36:37], 12, v[0:1]
	v_lshl_add_u64 v[36:37], v[42:43], 0, v[36:37]
	v_or_b32_e32 v0, 56, v40
	global_load_dwordx4 v[36:39], v[36:37], off nt
	v_lshlrev_b64 v[40:41], 12, v[0:1]
	v_lshl_add_u64 v[40:41], v[42:43], 0, v[40:41]
	global_load_dwordx4 v[40:43], v[40:41], off nt
	v_add_u32_e32 v0, v5, v10
	s_lshl_b64 s[6:7], s[44:45], 1
	s_add_u32 s6, s18, s6
	s_addc_u32 s7, s19, s7
	s_waitcnt vmcnt(0)
	ds_write2_b32 v0, v6, v7 offset1:1
	ds_write2_b32 v0, v8, v9 offset0:2 offset1:3
	v_add_u32_e32 v6, 0x420, v0
	ds_write2_b32 v6, v16, v17 offset1:1
	v_add_u32_e32 v6, 0x428, v0
	ds_write2_b32 v6, v18, v19 offset1:1
	v_add_u32_e32 v6, 0x840, v0
	ds_write2_b32 v6, v20, v21 offset1:1
	v_add_u32_e32 v6, 0x848, v0
	ds_write2_b32 v6, v22, v23 offset1:1
	v_add_u32_e32 v6, 0xc60, v0
	ds_write2_b32 v6, v24, v25 offset1:1
	v_add_u32_e32 v6, 0xc68, v0
	ds_write2_b32 v6, v26, v27 offset1:1
	v_add_u32_e32 v6, 0x1080, v0
	ds_write2_b32 v6, v28, v29 offset1:1
	v_add_u32_e32 v6, 0x1088, v0
	ds_write2_b32 v6, v30, v31 offset1:1
	v_add_u32_e32 v6, 0x14a0, v0
	ds_write2_b32 v6, v32, v33 offset1:1
	v_add_u32_e32 v6, 0x14a8, v0
	ds_write2_b32 v6, v34, v35 offset1:1
	v_add_u32_e32 v6, 0x18c0, v0
	ds_write2_b32 v6, v36, v37 offset1:1
	v_add_u32_e32 v6, 0x18c8, v0
	ds_write2_b32 v6, v38, v39 offset1:1
	v_add_u32_e32 v6, 0x1ce0, v0
	v_add_u32_e32 v0, 0x1ce8, v0
	ds_write2_b32 v6, v40, v41 offset1:1
	ds_write2_b32 v0, v42, v43 offset1:1
	s_waitcnt lgkmcnt(0)
	ds_read2_b32 v[8:9], v14 offset0:33 offset1:41
	ds_read2_b32 v[20:21], v14 offset1:8
	v_lshlrev_b32_e32 v0, 1, v4
	ds_read2_b32 v[22:23], v14 offset0:66 offset1:74
	ds_read2_b32 v[24:25], v14 offset0:99 offset1:107
	v_lshl_add_u64 v[6:7], s[6:7], 0, v[0:1]
	s_waitcnt lgkmcnt(3)
	v_bfe_u32 v15, v8, 16, 1
	s_waitcnt lgkmcnt(2)
	v_bfe_u32 v0, v20, 16, 1
	v_add3_u32 v0, v20, v0, s60
	v_lshrrev_b32_e32 v0, 16, v0
	v_add3_u32 v8, v8, v15, s60
	ds_read2_b32 v[26:27], v14 offset0:132 offset1:140
	ds_read2_b32 v[28:29], v14 offset0:165 offset1:173
	v_and_or_b32 v16, v8, s85, v0
	s_waitcnt lgkmcnt(3)
	v_bfe_u32 v0, v22, 16, 1
	v_add3_u32 v0, v22, v0, s60
	s_waitcnt lgkmcnt(2)
	v_bfe_u32 v8, v24, 16, 1
	v_lshrrev_b32_e32 v0, 16, v0
	v_add3_u32 v8, v24, v8, s60
	ds_read2_b32 v[30:31], v14 offset0:198 offset1:206
	ds_read2_b32 v[32:33], v14 offset0:231 offset1:239
	v_and_or_b32 v17, v8, s85, v0
	s_waitcnt lgkmcnt(3)
	v_bfe_u32 v0, v26, 16, 1
	v_add3_u32 v0, v26, v0, s60
	s_waitcnt lgkmcnt(2)
	v_bfe_u32 v8, v28, 16, 1
	v_lshrrev_b32_e32 v0, 16, v0
	v_add3_u32 v8, v28, v8, s60
	v_and_or_b32 v18, v8, s85, v0
	s_waitcnt lgkmcnt(1)
	v_bfe_u32 v0, v30, 16, 1
	v_add3_u32 v0, v30, v0, s60
	s_waitcnt lgkmcnt(0)
	v_bfe_u32 v8, v32, 16, 1
	v_lshrrev_b32_e32 v0, 16, v0
	v_add3_u32 v8, v32, v8, s60
	v_and_or_b32 v19, v8, s85, v0
	v_or_b32_e32 v0, s5, v3
	v_lshlrev_b32_e32 v0, 11, v0
	v_lshl_add_u64 v[34:35], v[6:7], 0, v[0:1]
	v_bfe_u32 v0, v21, 16, 1
	v_add3_u32 v0, v21, v0, s60
	v_bfe_u32 v8, v9, 16, 1
	v_lshrrev_b32_e32 v0, 16, v0
	v_add3_u32 v8, v9, v8, s60
	global_store_dwordx4 v[34:35], v[16:19], off sc1
	s_mov_b64 s[6:7], 0
	s_nop 0
	v_and_or_b32 v16, v8, s85, v0
	v_bfe_u32 v0, v23, 16, 1
	v_add3_u32 v0, v23, v0, s60
	v_bfe_u32 v8, v25, 16, 1
	v_lshrrev_b32_e32 v0, 16, v0
	v_add3_u32 v8, v25, v8, s60
	v_and_or_b32 v17, v8, s85, v0
	v_bfe_u32 v0, v27, 16, 1
	v_add3_u32 v0, v27, v0, s60
	v_bfe_u32 v8, v29, 16, 1
	v_lshrrev_b32_e32 v0, 16, v0
	v_add3_u32 v8, v29, v8, s60
	v_and_or_b32 v18, v8, s85, v0
	v_bfe_u32 v0, v31, 16, 1
	v_add3_u32 v0, v31, v0, s60
	v_bfe_u32 v8, v33, 16, 1
	v_lshrrev_b32_e32 v0, 16, v0
	v_add3_u32 v8, v33, v8, s60
	v_and_or_b32 v19, v8, s85, v0
	v_or_b32_e32 v0, s5, v11
	v_lshlrev_b32_e32 v0, 11, v0
	v_lshl_add_u64 v[8:9], v[6:7], 0, v[0:1]
	global_store_dwordx4 v[8:9], v[16:19], off sc1
	ds_read2_b32 v[8:9], v14 offset0:49 offset1:57
	ds_read2_b32 v[20:21], v14 offset0:16 offset1:24
	ds_read2_b32 v[22:23], v14 offset0:82 offset1:90
	ds_read2_b32 v[24:25], v14 offset0:115 offset1:123
	ds_read2_b32 v[26:27], v14 offset0:148 offset1:156
	ds_read2_b32 v[28:29], v14 offset0:181 offset1:189
	ds_read2_b32 v[30:31], v14 offset0:214 offset1:222
	ds_read2_b32 v[32:33], v14 offset0:247 offset1:255
	s_waitcnt lgkmcnt(7)
	v_bfe_u32 v15, v8, 16, 1
	s_waitcnt lgkmcnt(6)
	v_bfe_u32 v0, v20, 16, 1
	v_add3_u32 v0, v20, v0, s60
	v_lshrrev_b32_e32 v0, 16, v0
	v_add3_u32 v8, v8, v15, s60
	v_and_or_b32 v16, v8, s85, v0
	s_waitcnt lgkmcnt(5)
	v_bfe_u32 v0, v22, 16, 1
	v_add3_u32 v0, v22, v0, s60
	s_waitcnt lgkmcnt(4)
	v_bfe_u32 v8, v24, 16, 1
	v_lshrrev_b32_e32 v0, 16, v0
	v_add3_u32 v8, v24, v8, s60
	v_and_or_b32 v17, v8, s85, v0
	s_waitcnt lgkmcnt(3)
	v_bfe_u32 v0, v26, 16, 1
	v_add3_u32 v0, v26, v0, s60
	s_waitcnt lgkmcnt(2)
	v_bfe_u32 v8, v28, 16, 1
	v_lshrrev_b32_e32 v0, 16, v0
	v_add3_u32 v8, v28, v8, s60
	v_and_or_b32 v18, v8, s85, v0
	s_waitcnt lgkmcnt(1)
	v_bfe_u32 v0, v30, 16, 1
	v_add3_u32 v0, v30, v0, s60
	s_waitcnt lgkmcnt(0)
	v_bfe_u32 v8, v32, 16, 1
	v_lshrrev_b32_e32 v0, 16, v0
	v_add3_u32 v8, v32, v8, s60
	v_and_or_b32 v19, v8, s85, v0
	v_or_b32_e32 v0, s5, v12
	v_lshlrev_b32_e32 v0, 11, v0
	v_lshl_add_u64 v[34:35], v[6:7], 0, v[0:1]
	v_bfe_u32 v0, v21, 16, 1
	v_add3_u32 v0, v21, v0, s60
	v_bfe_u32 v8, v9, 16, 1
	v_lshrrev_b32_e32 v0, 16, v0
	v_add3_u32 v8, v9, v8, s60
	global_store_dwordx4 v[34:35], v[16:19], off sc1
	s_nop 1
	v_and_or_b32 v16, v8, s85, v0
	v_bfe_u32 v0, v23, 16, 1
	v_add3_u32 v0, v23, v0, s60
	v_bfe_u32 v8, v25, 16, 1
	v_lshrrev_b32_e32 v0, 16, v0
	v_add3_u32 v8, v25, v8, s60
	v_and_or_b32 v17, v8, s85, v0
	v_bfe_u32 v0, v27, 16, 1
	v_add3_u32 v0, v27, v0, s60
	v_bfe_u32 v8, v29, 16, 1
	v_lshrrev_b32_e32 v0, 16, v0
	v_add3_u32 v8, v29, v8, s60
	v_and_or_b32 v18, v8, s85, v0
	v_bfe_u32 v0, v31, 16, 1
	v_add3_u32 v0, v31, v0, s60
	v_bfe_u32 v8, v33, 16, 1
	v_lshrrev_b32_e32 v0, 16, v0
	v_add3_u32 v8, v33, v8, s60
	v_and_or_b32 v19, v8, s85, v0
	v_or_b32_e32 v0, s5, v13
	v_lshlrev_b32_e32 v0, 11, v0
	v_lshl_add_u64 v[6:7], v[6:7], 0, v[0:1]
	global_store_dwordx4 v[6:7], v[16:19], off sc1
	s_waitcnt lgkmcnt(0)
.LBB0_451:
	s_andn2_b64 vcc, exec, s[6:7]
	s_cbranch_vccnz .LBB0_453
	s_add_i32 s5, s15, 0xdf00
	s_and_b32 s6, s5, 0xffff
	s_mul_i32 s6, s6, 0xcccd
	s_lshr_b32 s16, s6, 16
	s_lshr_b32 s6, s6, 22
	s_mulk_i32 s6, 0x50
	s_sub_i32 s5, s5, s6
	s_load_dwordx2 s[6:7], s[8:9], 0x70
	s_mul_i32 s18, s4, 0xa00000
	s_mul_hi_i32 s17, s4, 0xa00000
	v_lshlrev_b32_e32 v0, 2, v2
	s_waitcnt lgkmcnt(0)
	s_add_u32 s6, s6, s18
	s_addc_u32 s7, s7, s17
	s_mul_i32 s18, s4, 0x500000
	s_mul_hi_i32 s17, s4, 0x500000
	s_add_u32 s18, s2, s18
	s_addc_u32 s17, s3, s17
	s_lshl_b32 s5, s5, 5
	s_and_b32 s5, s5, 0xffe0
	s_and_b32 s16, s16, 0xffc0
	s_lshl_b32 s19, s5, 2
	s_add_u32 s6, s6, s19
	v_or_b32_e32 v8, s16, v3
	s_addc_u32 s7, s7, 0
	v_lshl_add_u64 v[6:7], s[6:7], 0, v[0:1]
	v_mul_u32_u24_e32 v0, 0xa00, v8
	v_lshlrev_b32_e32 v0, 2, v0
	v_lshl_add_u64 v[40:41], v[6:7], 0, v[0:1]
	s_mov_b32 s6, 0x14000
	v_add_co_u32_e32 v16, vcc, s6, v40
	global_load_dwordx4 v[6:9], v[40:41], off nt
	s_nop 0
	v_addc_co_u32_e32 v17, vcc, 0, v41, vcc
	s_mov_b32 s6, 0x28000
	global_load_dwordx4 v[16:19], v[16:17], off nt
	v_add_co_u32_e32 v20, vcc, s6, v40
	s_mov_b32 s6, 0x3c000
	s_nop 0
	v_addc_co_u32_e32 v21, vcc, 0, v41, vcc
	global_load_dwordx4 v[20:23], v[20:21], off nt
	v_add_co_u32_e32 v24, vcc, s6, v40
	s_mov_b32 s6, 0x50000
	s_nop 0
	v_addc_co_u32_e32 v25, vcc, 0, v41, vcc
	global_load_dwordx4 v[24:27], v[24:25], off nt
	v_add_co_u32_e32 v28, vcc, s6, v40
	s_mov_b32 s6, 0x64000
	s_nop 0
	v_addc_co_u32_e32 v29, vcc, 0, v41, vcc
	global_load_dwordx4 v[28:31], v[28:29], off nt
	v_add_co_u32_e32 v32, vcc, s6, v40
	s_mov_b32 s6, 0x78000
	s_nop 0
	v_addc_co_u32_e32 v33, vcc, 0, v41, vcc
	global_load_dwordx4 v[32:35], v[32:33], off nt
	v_add_co_u32_e32 v36, vcc, s6, v40
	s_mov_b32 s6, 0x8c000
	s_nop 0
	v_addc_co_u32_e32 v37, vcc, 0, v41, vcc
	global_load_dwordx4 v[36:39], v[36:37], off nt
	v_add_co_u32_e32 v40, vcc, s6, v40
	v_add_u32_e32 v0, v5, v10
	s_nop 0
	v_addc_co_u32_e32 v41, vcc, 0, v41, vcc
	global_load_dwordx4 v[40:43], v[40:41], off nt
	s_lshl_b32 s6, s16, 1
	s_add_u32 s6, s18, s6
	s_addc_u32 s7, s17, 0
	s_waitcnt vmcnt(0)
	ds_write2_b32 v0, v6, v7 offset1:1
	ds_write2_b32 v0, v8, v9 offset0:2 offset1:3
	v_add_u32_e32 v6, 0x420, v0
	ds_write2_b32 v6, v16, v17 offset1:1
	v_add_u32_e32 v6, 0x428, v0
	ds_write2_b32 v6, v18, v19 offset1:1
	v_add_u32_e32 v6, 0x840, v0
	ds_write2_b32 v6, v20, v21 offset1:1
	v_add_u32_e32 v6, 0x848, v0
	ds_write2_b32 v6, v22, v23 offset1:1
	v_add_u32_e32 v6, 0xc60, v0
	ds_write2_b32 v6, v24, v25 offset1:1
	v_add_u32_e32 v6, 0xc68, v0
	ds_write2_b32 v6, v26, v27 offset1:1
	v_add_u32_e32 v6, 0x1080, v0
	ds_write2_b32 v6, v28, v29 offset1:1
	v_add_u32_e32 v6, 0x1088, v0
	ds_write2_b32 v6, v30, v31 offset1:1
	v_add_u32_e32 v6, 0x14a0, v0
	ds_write2_b32 v6, v32, v33 offset1:1
	v_add_u32_e32 v6, 0x14a8, v0
	ds_write2_b32 v6, v34, v35 offset1:1
	v_add_u32_e32 v6, 0x18c0, v0
	ds_write2_b32 v6, v36, v37 offset1:1
	v_add_u32_e32 v6, 0x18c8, v0
	ds_write2_b32 v6, v38, v39 offset1:1
	v_add_u32_e32 v6, 0x1ce0, v0
	v_add_u32_e32 v0, 0x1ce8, v0
	ds_write2_b32 v6, v40, v41 offset1:1
	ds_write2_b32 v0, v42, v43 offset1:1
	s_waitcnt lgkmcnt(0)
	ds_read2_b32 v[8:9], v14 offset0:33 offset1:41
	ds_read2_b32 v[20:21], v14 offset1:8
	v_lshlrev_b32_e32 v0, 1, v4
	ds_read2_b32 v[22:23], v14 offset0:66 offset1:74
	ds_read2_b32 v[24:25], v14 offset0:99 offset1:107
	v_lshl_add_u64 v[6:7], s[6:7], 0, v[0:1]
	s_waitcnt lgkmcnt(3)
	v_bfe_u32 v15, v8, 16, 1
	s_waitcnt lgkmcnt(2)
	v_bfe_u32 v0, v20, 16, 1
	v_add3_u32 v0, v20, v0, s60
	v_lshrrev_b32_e32 v0, 16, v0
	v_add3_u32 v8, v8, v15, s60
	ds_read2_b32 v[26:27], v14 offset0:132 offset1:140
	ds_read2_b32 v[28:29], v14 offset0:165 offset1:173
	v_and_or_b32 v16, v8, s85, v0
	s_waitcnt lgkmcnt(3)
	v_bfe_u32 v0, v22, 16, 1
	v_add3_u32 v0, v22, v0, s60
	s_waitcnt lgkmcnt(2)
	v_bfe_u32 v8, v24, 16, 1
	v_lshrrev_b32_e32 v0, 16, v0
	v_add3_u32 v8, v24, v8, s60
	ds_read2_b32 v[30:31], v14 offset0:198 offset1:206
	ds_read2_b32 v[32:33], v14 offset0:231 offset1:239
	v_and_or_b32 v17, v8, s85, v0
	s_waitcnt lgkmcnt(3)
	v_bfe_u32 v0, v26, 16, 1
	v_add3_u32 v0, v26, v0, s60
	s_waitcnt lgkmcnt(2)
	v_bfe_u32 v8, v28, 16, 1
	v_lshrrev_b32_e32 v0, 16, v0
	v_add3_u32 v8, v28, v8, s60
	v_and_or_b32 v18, v8, s85, v0
	s_waitcnt lgkmcnt(1)
	v_bfe_u32 v0, v30, 16, 1
	v_add3_u32 v0, v30, v0, s60
	s_waitcnt lgkmcnt(0)
	v_bfe_u32 v8, v32, 16, 1
	v_lshrrev_b32_e32 v0, 16, v0
	v_add3_u32 v8, v32, v8, s60
	v_and_or_b32 v19, v8, s85, v0
	v_or_b32_e32 v0, s5, v3
	v_lshlrev_b32_e32 v0, 11, v0
	v_lshl_add_u64 v[34:35], v[6:7], 0, v[0:1]
	v_bfe_u32 v0, v21, 16, 1
	v_add3_u32 v0, v21, v0, s60
	v_bfe_u32 v8, v9, 16, 1
	v_lshrrev_b32_e32 v0, 16, v0
	v_add3_u32 v8, v9, v8, s60
	global_store_dwordx4 v[34:35], v[16:19], off sc1
	s_nop 1
	v_and_or_b32 v16, v8, s85, v0
	v_bfe_u32 v0, v23, 16, 1
	v_add3_u32 v0, v23, v0, s60
	v_bfe_u32 v8, v25, 16, 1
	v_lshrrev_b32_e32 v0, 16, v0
	v_add3_u32 v8, v25, v8, s60
	v_and_or_b32 v17, v8, s85, v0
	v_bfe_u32 v0, v27, 16, 1
	v_add3_u32 v0, v27, v0, s60
	v_bfe_u32 v8, v29, 16, 1
	v_lshrrev_b32_e32 v0, 16, v0
	v_add3_u32 v8, v29, v8, s60
	v_and_or_b32 v18, v8, s85, v0
	v_bfe_u32 v0, v31, 16, 1
	v_add3_u32 v0, v31, v0, s60
	v_bfe_u32 v8, v33, 16, 1
	v_lshrrev_b32_e32 v0, 16, v0
	v_add3_u32 v8, v33, v8, s60
	v_and_or_b32 v19, v8, s85, v0
	v_or_b32_e32 v0, s5, v11
	v_lshlrev_b32_e32 v0, 11, v0
	v_lshl_add_u64 v[8:9], v[6:7], 0, v[0:1]
	global_store_dwordx4 v[8:9], v[16:19], off sc1
	ds_read2_b32 v[8:9], v14 offset0:49 offset1:57
	ds_read2_b32 v[20:21], v14 offset0:16 offset1:24
	ds_read2_b32 v[22:23], v14 offset0:82 offset1:90
	ds_read2_b32 v[24:25], v14 offset0:115 offset1:123
	ds_read2_b32 v[26:27], v14 offset0:148 offset1:156
	ds_read2_b32 v[28:29], v14 offset0:181 offset1:189
	ds_read2_b32 v[30:31], v14 offset0:214 offset1:222
	ds_read2_b32 v[32:33], v14 offset0:247 offset1:255
	s_waitcnt lgkmcnt(7)
	v_bfe_u32 v15, v8, 16, 1
	s_waitcnt lgkmcnt(6)
	v_bfe_u32 v0, v20, 16, 1
	v_add3_u32 v0, v20, v0, s60
	v_lshrrev_b32_e32 v0, 16, v0
	v_add3_u32 v8, v8, v15, s60
	v_and_or_b32 v16, v8, s85, v0
	s_waitcnt lgkmcnt(5)
	v_bfe_u32 v0, v22, 16, 1
	v_add3_u32 v0, v22, v0, s60
	s_waitcnt lgkmcnt(4)
	v_bfe_u32 v8, v24, 16, 1
	v_lshrrev_b32_e32 v0, 16, v0
	v_add3_u32 v8, v24, v8, s60
	v_and_or_b32 v17, v8, s85, v0
	s_waitcnt lgkmcnt(3)
	v_bfe_u32 v0, v26, 16, 1
	v_add3_u32 v0, v26, v0, s60
	s_waitcnt lgkmcnt(2)
	v_bfe_u32 v8, v28, 16, 1
	v_lshrrev_b32_e32 v0, 16, v0
	v_add3_u32 v8, v28, v8, s60
	v_and_or_b32 v18, v8, s85, v0
	s_waitcnt lgkmcnt(1)
	v_bfe_u32 v0, v30, 16, 1
	v_add3_u32 v0, v30, v0, s60
	s_waitcnt lgkmcnt(0)
	v_bfe_u32 v8, v32, 16, 1
	v_lshrrev_b32_e32 v0, 16, v0
	v_add3_u32 v8, v32, v8, s60
	v_and_or_b32 v19, v8, s85, v0
	v_or_b32_e32 v0, s5, v12
	v_lshlrev_b32_e32 v0, 11, v0
	v_lshl_add_u64 v[34:35], v[6:7], 0, v[0:1]
	v_bfe_u32 v0, v21, 16, 1
	v_add3_u32 v0, v21, v0, s60
	v_bfe_u32 v8, v9, 16, 1
	v_lshrrev_b32_e32 v0, 16, v0
	v_add3_u32 v8, v9, v8, s60
	global_store_dwordx4 v[34:35], v[16:19], off sc1
	s_nop 1
	v_and_or_b32 v16, v8, s85, v0
	v_bfe_u32 v0, v23, 16, 1
	v_add3_u32 v0, v23, v0, s60
	v_bfe_u32 v8, v25, 16, 1
	v_lshrrev_b32_e32 v0, 16, v0
	v_add3_u32 v8, v25, v8, s60
	v_and_or_b32 v17, v8, s85, v0
	v_bfe_u32 v0, v27, 16, 1
	v_add3_u32 v0, v27, v0, s60
	v_bfe_u32 v8, v29, 16, 1
	v_lshrrev_b32_e32 v0, 16, v0
	v_add3_u32 v8, v29, v8, s60
	v_and_or_b32 v18, v8, s85, v0
	v_bfe_u32 v0, v31, 16, 1
	v_add3_u32 v0, v31, v0, s60
	v_bfe_u32 v8, v33, 16, 1
	v_lshrrev_b32_e32 v0, 16, v0
	v_add3_u32 v8, v33, v8, s60
	v_and_or_b32 v19, v8, s85, v0
	v_or_b32_e32 v0, s5, v13
	v_lshlrev_b32_e32 v0, 11, v0
	v_lshl_add_u64 v[6:7], v[6:7], 0, v[0:1]
	global_store_dwordx4 v[6:7], v[16:19], off sc1
	s_waitcnt lgkmcnt(0)

.LBB0_454:
	s_andn2_b64 vcc, exec, s[6:7]
	s_cbranch_vccnz .LBB0_447
	s_mul_i32 s5, s15, 0xba3
	s_lshr_b32 s6, s5, 31
	s_ashr_i32 s5, s5, 22
	s_add_i32 s5, s5, s6
	s_mul_i32 s6, s5, 0x580
	s_sub_i32 s16, s15, s6
	v_add_u32_e32 v15, v5, v10
	s_mov_b64 s[6:7], -1
	s_cmpk_gt_i32 s15, 0x15ff
	s_sext_i32_i16 s15, s16
	v_lshlrev_b32_e32 v0, 2, v2
	v_add_u32_e32 v16, 0x420, v15
	v_add_u32_e32 v17, 0x428, v15
	v_add_u32_e32 v18, 0x840, v15
	v_add_u32_e32 v19, 0x848, v15
	v_add_u32_e32 v20, 0xc60, v15
	v_add_u32_e32 v21, 0xc68, v15
	v_add_u32_e32 v22, 0x1080, v15
	v_add_u32_e32 v23, 0x1088, v15
	v_add_u32_e32 v24, 0x14a0, v15
	v_add_u32_e32 v25, 0x14a8, v15
	v_add_u32_e32 v26, 0x18c0, v15
	v_add_u32_e32 v27, 0x18c8, v15
	v_add_u32_e32 v28, 0x1ce0, v15
	v_add_u32_e32 v29, 0x1ce8, v15
	v_lshlrev_b32_e32 v6, 1, v4
	s_cbranch_scc0 .LBB0_457
	s_load_dwordx2 s[6:7], s[8:9], 0x68
	s_lshl_b32 s17, s4, 1
	s_add_i32 s17, s17, s5
	s_add_i32 s17, s17, -4
	s_mul_i32 s19, s17, 0xb00000
	s_mul_hi_i32 s18, s17, 0xb00000
	s_waitcnt lgkmcnt(0)
	s_add_u32 s19, s6, s19
	s_addc_u32 s7, s7, s18
	s_mul_hi_i32 s6, s17, 0x580000
	s_mul_i32 s17, s17, 0x580000
	s_add_u32 s17, s12, s17
	s_addc_u32 s20, s13, s6
	s_lshl_b32 s6, s15, 1
	s_and_b32 s21, s6, 0xfc0
	s_lshl_b32 s6, s15, 5
	s_and_b32 s6, s6, 0x3e0
	s_lshl_b32 s18, s6, 2
	s_add_u32 s18, s19, s18
	v_or_b32_e32 v7, s21, v3
	s_addc_u32 s19, s7, 0
	v_lshl_add_u64 v[8:9], s[18:19], 0, v[0:1]
	v_lshlrev_b32_e32 v30, 12, v7
	v_mov_b32_e32 v31, v1
	v_lshl_add_u64 v[8:9], v[8:9], 0, v[30:31]
	s_mov_b32 s7, 0x8000
	global_load_dwordx4 v[30:33], v[8:9], off nt
	v_add_co_u32_e32 v34, vcc, s7, v8
	s_mov_b32 s7, 0x10000
	s_nop 0
	v_addc_co_u32_e32 v35, vcc, 0, v9, vcc
	global_load_dwordx4 v[34:37], v[34:35], off nt
	v_add_co_u32_e32 v38, vcc, s7, v8
	s_mov_b32 s7, 0x18000
	s_nop 0
	v_addc_co_u32_e32 v39, vcc, 0, v9, vcc
	global_load_dwordx4 v[38:41], v[38:39], off nt
	v_add_co_u32_e32 v42, vcc, s7, v8
	s_mov_b32 s7, 0x20000
	s_nop 0
	v_addc_co_u32_e32 v43, vcc, 0, v9, vcc
	global_load_dwordx4 v[42:45], v[42:43], off nt
	v_add_co_u32_e32 v46, vcc, s7, v8
	s_mov_b32 s7, 0x28000
	s_nop 0
	v_addc_co_u32_e32 v47, vcc, 0, v9, vcc
	global_load_dwordx4 v[46:49], v[46:47], off nt
	v_add_co_u32_e32 v50, vcc, s7, v8
	s_mov_b32 s7, 0x30000
	s_nop 0
	v_addc_co_u32_e32 v51, vcc, 0, v9, vcc
	global_load_dwordx4 v[50:53], v[50:51], off nt
	v_add_co_u32_e32 v54, vcc, s7, v8
	s_mov_b32 s7, 0x38000
	s_nop 0
	v_addc_co_u32_e32 v55, vcc, 0, v9, vcc
	global_load_dwordx4 v[54:57], v[54:55], off nt
	v_add_co_u32_e32 v8, vcc, s7, v8
	s_lshl_b32 s7, s21, 1
	s_nop 0
	v_addc_co_u32_e32 v9, vcc, 0, v9, vcc
	global_load_dwordx4 v[58:61], v[8:9], off nt
	s_add_u32 s18, s17, s7
	s_addc_u32 s19, s20, 0
	v_mov_b32_e32 v7, v1
	v_lshl_add_u64 v[8:9], s[18:19], 0, v[6:7]
	s_waitcnt vmcnt(0)
	ds_write2_b32 v15, v30, v31 offset1:1
	ds_write2_b32 v15, v32, v33 offset0:2 offset1:3
	ds_write2_b32 v16, v34, v35 offset1:1
	ds_write2_b32 v17, v36, v37 offset1:1
	ds_write2_b32 v18, v38, v39 offset1:1
	ds_write2_b32 v19, v40, v41 offset1:1
	ds_write2_b32 v20, v42, v43 offset1:1
	ds_write2_b32 v21, v44, v45 offset1:1
	ds_write2_b32 v22, v46, v47 offset1:1
	ds_write2_b32 v23, v48, v49 offset1:1
	ds_write2_b32 v24, v50, v51 offset1:1
	ds_write2_b32 v25, v52, v53 offset1:1
	ds_write2_b32 v26, v54, v55 offset1:1
	ds_write2_b32 v27, v56, v57 offset1:1
	ds_write2_b32 v28, v58, v59 offset1:1
	ds_write2_b32 v29, v60, v61 offset1:1
	s_waitcnt lgkmcnt(0)
	ds_read2_b32 v[34:35], v14 offset0:33 offset1:41
	ds_read2_b32 v[36:37], v14 offset1:8
	ds_read2_b32 v[38:39], v14 offset0:66 offset1:74
	ds_read2_b32 v[40:41], v14 offset0:99 offset1:107
	ds_read2_b32 v[42:43], v14 offset0:132 offset1:140
	ds_read2_b32 v[44:45], v14 offset0:165 offset1:173
	ds_read2_b32 v[46:47], v14 offset0:198 offset1:206
	ds_read2_b32 v[48:49], v14 offset0:231 offset1:239
	s_waitcnt lgkmcnt(7)
	v_bfe_u32 v30, v34, 16, 1
	s_waitcnt lgkmcnt(6)
	v_bfe_u32 v7, v36, 16, 1
	v_add3_u32 v7, v36, v7, s60
	v_lshrrev_b32_e32 v7, 16, v7
	v_add3_u32 v30, v34, v30, s60
	v_and_or_b32 v30, v30, s85, v7
	s_waitcnt lgkmcnt(5)
	v_bfe_u32 v7, v38, 16, 1
	v_add3_u32 v7, v38, v7, s60
	s_waitcnt lgkmcnt(4)
	v_bfe_u32 v31, v40, 16, 1
	v_lshrrev_b32_e32 v7, 16, v7
	v_add3_u32 v31, v40, v31, s60
	v_and_or_b32 v31, v31, s85, v7
	s_waitcnt lgkmcnt(3)
	v_bfe_u32 v7, v42, 16, 1
	v_add3_u32 v7, v42, v7, s60
	s_waitcnt lgkmcnt(2)
	v_bfe_u32 v32, v44, 16, 1
	v_lshrrev_b32_e32 v7, 16, v7
	v_add3_u32 v32, v44, v32, s60
	v_and_or_b32 v32, v32, s85, v7
	s_waitcnt lgkmcnt(1)
	v_bfe_u32 v7, v46, 16, 1
	v_add3_u32 v7, v46, v7, s60
	s_waitcnt lgkmcnt(0)
	v_bfe_u32 v33, v48, 16, 1
	v_lshrrev_b32_e32 v7, 16, v7
	v_add3_u32 v33, v48, v33, s60
	v_and_or_b32 v33, v33, s85, v7
	v_or_b32_e32 v7, s6, v3
	v_mul_u32_u24_e32 v7, 0xb00, v7
	v_lshlrev_b32_e32 v50, 1, v7
	v_mov_b32_e32 v51, v1
	v_lshl_add_u64 v[50:51], v[8:9], 0, v[50:51]
	v_bfe_u32 v7, v37, 16, 1
	global_store_dwordx4 v[50:51], v[30:33], off sc1
	v_add3_u32 v7, v37, v7, s60
	v_lshrrev_b32_e32 v7, 16, v7
	v_bfe_u32 v30, v35, 16, 1
	v_add3_u32 v30, v35, v30, s60
	v_and_or_b32 v30, v30, s85, v7
	v_bfe_u32 v7, v39, 16, 1
	v_add3_u32 v7, v39, v7, s60
	v_bfe_u32 v31, v41, 16, 1
	v_lshrrev_b32_e32 v7, 16, v7
	v_add3_u32 v31, v41, v31, s60
	v_and_or_b32 v31, v31, s85, v7
	v_bfe_u32 v7, v43, 16, 1
	v_add3_u32 v7, v43, v7, s60
	v_bfe_u32 v32, v45, 16, 1
	v_lshrrev_b32_e32 v7, 16, v7
	v_add3_u32 v32, v45, v32, s60
	v_and_or_b32 v32, v32, s85, v7
	v_bfe_u32 v7, v47, 16, 1
	v_add3_u32 v7, v47, v7, s60
	v_bfe_u32 v33, v49, 16, 1
	v_lshrrev_b32_e32 v7, 16, v7
	v_add3_u32 v33, v49, v33, s60
	v_and_or_b32 v33, v33, s85, v7
	v_or_b32_e32 v7, s6, v11
	v_mul_u32_u24_e32 v7, 0xb00, v7
	v_lshlrev_b32_e32 v34, 1, v7
	v_mov_b32_e32 v35, v1
	v_lshl_add_u64 v[34:35], v[8:9], 0, v[34:35]
	global_store_dwordx4 v[34:35], v[30:33], off sc1
	ds_read2_b32 v[34:35], v14 offset0:16 offset1:24
	ds_read2_b32 v[36:37], v14 offset0:49 offset1:57
	ds_read2_b32 v[38:39], v14 offset0:82 offset1:90
	ds_read2_b32 v[40:41], v14 offset0:115 offset1:123
	ds_read2_b32 v[42:43], v14 offset0:148 offset1:156
	ds_read2_b32 v[44:45], v14 offset0:181 offset1:189
	ds_read2_b32 v[46:47], v14 offset0:214 offset1:222
	ds_read2_b32 v[48:49], v14 offset0:247 offset1:255
	s_waitcnt lgkmcnt(7)
	v_bfe_u32 v7, v34, 16, 1
	v_add3_u32 v7, v34, v7, s60
	s_waitcnt lgkmcnt(6)
	v_bfe_u32 v30, v36, 16, 1
	v_lshrrev_b32_e32 v7, 16, v7
	v_add3_u32 v30, v36, v30, s60
	v_and_or_b32 v30, v30, s85, v7
	s_waitcnt lgkmcnt(5)
	v_bfe_u32 v7, v38, 16, 1
	v_add3_u32 v7, v38, v7, s60
	s_waitcnt lgkmcnt(4)
	v_bfe_u32 v31, v40, 16, 1
	v_lshrrev_b32_e32 v7, 16, v7
	v_add3_u32 v31, v40, v31, s60
	v_and_or_b32 v31, v31, s85, v7
	s_waitcnt lgkmcnt(3)
	v_bfe_u32 v7, v42, 16, 1
	v_add3_u32 v7, v42, v7, s60
	s_waitcnt lgkmcnt(2)
	v_bfe_u32 v32, v44, 16, 1
	v_lshrrev_b32_e32 v7, 16, v7
	v_add3_u32 v32, v44, v32, s60
	v_and_or_b32 v32, v32, s85, v7
	s_waitcnt lgkmcnt(1)
	v_bfe_u32 v7, v46, 16, 1
	v_add3_u32 v7, v46, v7, s60
	s_waitcnt lgkmcnt(0)
	v_bfe_u32 v33, v48, 16, 1
	v_lshrrev_b32_e32 v7, 16, v7
	v_add3_u32 v33, v48, v33, s60
	v_and_or_b32 v33, v33, s85, v7
	v_or_b32_e32 v7, s6, v12
	v_mul_u32_u24_e32 v7, 0xb00, v7
	v_lshlrev_b32_e32 v50, 1, v7
	v_mov_b32_e32 v51, v1
	v_lshl_add_u64 v[50:51], v[8:9], 0, v[50:51]
	v_bfe_u32 v7, v35, 16, 1
	global_store_dwordx4 v[50:51], v[30:33], off sc1
	v_add3_u32 v7, v35, v7, s60
	v_lshrrev_b32_e32 v7, 16, v7
	v_bfe_u32 v30, v37, 16, 1
	v_add3_u32 v30, v37, v30, s60
	v_and_or_b32 v30, v30, s85, v7
	v_bfe_u32 v7, v39, 16, 1
	v_add3_u32 v7, v39, v7, s60
	v_bfe_u32 v31, v41, 16, 1
	v_lshrrev_b32_e32 v7, 16, v7
	v_add3_u32 v31, v41, v31, s60
	v_and_or_b32 v31, v31, s85, v7
	v_bfe_u32 v7, v43, 16, 1
	v_add3_u32 v7, v43, v7, s60
	v_bfe_u32 v32, v45, 16, 1
	v_lshrrev_b32_e32 v7, 16, v7
	v_add3_u32 v32, v45, v32, s60
	v_and_or_b32 v32, v32, s85, v7
	v_bfe_u32 v7, v47, 16, 1
	v_add3_u32 v7, v47, v7, s60
	v_bfe_u32 v33, v49, 16, 1
	v_lshrrev_b32_e32 v7, 16, v7
	v_add3_u32 v33, v49, v33, s60
	v_and_or_b32 v33, v33, s85, v7
	v_or_b32_e32 v7, s6, v13
	v_mul_u32_u24_e32 v7, 0xb00, v7
	v_lshlrev_b32_e32 v34, 1, v7
	v_mov_b32_e32 v35, v1
	v_lshl_add_u64 v[8:9], v[8:9], 0, v[34:35]
	global_store_dwordx4 v[8:9], v[30:33], off sc1
	s_waitcnt lgkmcnt(0)
	s_mov_b64 s[6:7], 0
.LBB0_457:
	s_andn2_b64 vcc, exec, s[6:7]
	s_cbranch_vccnz .LBB0_447
	s_and_b32 s17, s5, 1
	s_and_b32 s6, s5, 0xffff
	s_cmp_lt_u32 s6, 2
	s_movk_i32 s6, 0x60
	s_cselect_b32 s6, 0x58, s6
	s_add_u32 s6, s8, s6
	s_addc_u32 s7, s9, 0
	s_load_dwordx2 s[6:7], s[6:7], 0x0
	s_lshl_b32 s4, s4, 1
	s_or_b32 s4, s17, s4
	s_mul_i32 s18, s4, 0xb00000
	s_mul_hi_i32 s17, s4, 0xb00000
	s_waitcnt lgkmcnt(0)
	s_add_u32 s19, s6, s18
	s_mulk_i32 s15, 0xba3
	s_addc_u32 s7, s7, s17
	s_lshr_b32 s4, s15, 31
	s_ashr_i32 s6, s15, 18
	s_add_i32 s4, s6, s4
	s_sext_i32_i16 s6, s4
	s_mulk_i32 s4, 0x58
	s_sub_i32 s4, s16, s4
	s_sext_i32_i16 s15, s4
	s_lshl_b32 s4, s15, 5
	s_add_u32 s18, s10, s18
	s_addc_u32 s20, s11, s17
	s_lshl_b32 s16, s6, 6
	s_lshl_b32 s6, s15, 6
	s_lshl_b32 s5, s5, 6
	s_and_b32 s6, s6, 0xffffff00
	s_and_b32 s5, s5, 0xffffff80
	s_add_i32 s6, s6, s5
	s_and_b32 s5, s4, 0x60
	s_or_b32 s6, s6, s5
	s_ashr_i32 s5, s4, 31
	s_lshl_b64 s[4:5], s[4:5], 2
	v_or_b32_e32 v7, s16, v3
	s_add_u32 s4, s19, s4
	s_addc_u32 s5, s7, s5
	v_mul_i32_i24_e32 v30, 0xb00, v7
	v_lshl_add_u64 v[8:9], s[4:5], 0, v[0:1]
	v_ashrrev_i32_e32 v31, 31, v30
	v_lshl_add_u64 v[8:9], v[30:31], 2, v[8:9]
	s_mov_b32 s4, 0x16000
	global_load_dwordx4 v[30:33], v[8:9], off nt
	v_add_co_u32_e32 v34, vcc, s4, v8
	s_mov_b32 s4, 0x2c000
	s_nop 0
	v_addc_co_u32_e32 v35, vcc, 0, v9, vcc
	global_load_dwordx4 v[34:37], v[34:35], off nt
	v_add_co_u32_e32 v38, vcc, s4, v8
	s_mov_b32 s4, 0x42000
	s_nop 0
	v_addc_co_u32_e32 v39, vcc, 0, v9, vcc
	global_load_dwordx4 v[38:41], v[38:39], off nt
	v_add_co_u32_e32 v42, vcc, s4, v8
	s_mov_b32 s4, 0x58000
	s_nop 0
	v_addc_co_u32_e32 v43, vcc, 0, v9, vcc
	global_load_dwordx4 v[42:45], v[42:43], off nt
	v_add_co_u32_e32 v46, vcc, s4, v8
	s_mov_b32 s4, 0x6e000
	s_nop 0
	v_addc_co_u32_e32 v47, vcc, 0, v9, vcc
	global_load_dwordx4 v[46:49], v[46:47], off nt
	v_add_co_u32_e32 v50, vcc, s4, v8
	s_mov_b32 s4, 0x84000
	s_nop 0
	v_addc_co_u32_e32 v51, vcc, 0, v9, vcc
	global_load_dwordx4 v[50:53], v[50:51], off nt
	v_add_co_u32_e32 v54, vcc, s4, v8
	s_mov_b32 s4, 0x9a000
	s_nop 0
	v_addc_co_u32_e32 v55, vcc, 0, v9, vcc
	global_load_dwordx4 v[54:57], v[54:55], off nt
	v_add_co_u32_e32 v8, vcc, s4, v8
	s_ashr_i32 s17, s16, 31
	s_nop 0
	v_addc_co_u32_e32 v9, vcc, 0, v9, vcc
	global_load_dwordx4 v[58:61], v[8:9], off nt
	s_lshl_b64 s[4:5], s[16:17], 1
	s_add_u32 s4, s18, s4
	s_addc_u32 s5, s20, s5
	v_mov_b32_e32 v7, v1
	v_lshl_add_u64 v[6:7], s[4:5], 0, v[6:7]
	s_waitcnt vmcnt(0)
	ds_write2_b32 v15, v30, v31 offset1:1
	ds_write2_b32 v15, v32, v33 offset0:2 offset1:3
	ds_write2_b32 v16, v34, v35 offset1:1
	ds_write2_b32 v17, v36, v37 offset1:1
	ds_write2_b32 v18, v38, v39 offset1:1
	ds_write2_b32 v19, v40, v41 offset1:1
	ds_write2_b32 v20, v42, v43 offset1:1
	ds_write2_b32 v21, v44, v45 offset1:1
	ds_write2_b32 v22, v46, v47 offset1:1
	ds_write2_b32 v23, v48, v49 offset1:1
	ds_write2_b32 v24, v50, v51 offset1:1
	ds_write2_b32 v25, v52, v53 offset1:1
	ds_write2_b32 v26, v54, v55 offset1:1
	ds_write2_b32 v27, v56, v57 offset1:1
	ds_write2_b32 v28, v58, v59 offset1:1
	ds_write2_b32 v29, v60, v61 offset1:1
	s_waitcnt lgkmcnt(0)
	ds_read2_b32 v[8:9], v14 offset0:33 offset1:41
	ds_read2_b32 v[20:21], v14 offset1:8
	ds_read2_b32 v[22:23], v14 offset0:66 offset1:74
	ds_read2_b32 v[24:25], v14 offset0:99 offset1:107
	ds_read2_b32 v[26:27], v14 offset0:132 offset1:140
	ds_read2_b32 v[28:29], v14 offset0:165 offset1:173
	ds_read2_b32 v[30:31], v14 offset0:198 offset1:206
	ds_read2_b32 v[32:33], v14 offset0:231 offset1:239
	s_waitcnt lgkmcnt(7)
	v_bfe_u32 v15, v8, 16, 1
	s_waitcnt lgkmcnt(6)
	v_bfe_u32 v0, v20, 16, 1
	v_add3_u32 v0, v20, v0, s60
	v_lshrrev_b32_e32 v0, 16, v0
	v_add3_u32 v8, v8, v15, s60
	v_and_or_b32 v16, v8, s85, v0
	s_waitcnt lgkmcnt(5)
	v_bfe_u32 v0, v22, 16, 1
	v_add3_u32 v0, v22, v0, s60
	s_waitcnt lgkmcnt(4)
	v_bfe_u32 v8, v24, 16, 1
	v_lshrrev_b32_e32 v0, 16, v0
	v_add3_u32 v8, v24, v8, s60
	v_and_or_b32 v17, v8, s85, v0
	s_waitcnt lgkmcnt(3)
	v_bfe_u32 v0, v26, 16, 1
	v_add3_u32 v0, v26, v0, s60
	s_waitcnt lgkmcnt(2)
	v_bfe_u32 v8, v28, 16, 1
	v_lshrrev_b32_e32 v0, 16, v0
	v_add3_u32 v8, v28, v8, s60
	v_and_or_b32 v18, v8, s85, v0
	s_waitcnt lgkmcnt(1)
	v_bfe_u32 v0, v30, 16, 1
	v_add3_u32 v0, v30, v0, s60
	s_waitcnt lgkmcnt(0)
	v_bfe_u32 v8, v32, 16, 1
	v_lshrrev_b32_e32 v0, 16, v0
	v_add3_u32 v8, v32, v8, s60
	v_or_b32_e32 v34, s6, v3
	v_and_or_b32 v19, v8, s85, v0
	v_ashrrev_i32_e32 v35, 31, v34
	v_bfe_u32 v0, v21, 16, 1
	v_lshlrev_b64 v[34:35], 11, v[34:35]
	v_add3_u32 v0, v21, v0, s60
	v_bfe_u32 v8, v9, 16, 1
	v_lshl_add_u64 v[34:35], v[6:7], 0, v[34:35]
	v_lshrrev_b32_e32 v0, 16, v0
	v_add3_u32 v8, v9, v8, s60
	global_store_dwordx4 v[34:35], v[16:19], off sc1
	v_or_b32_e32 v34, s6, v12
	v_ashrrev_i32_e32 v35, 31, v34
	v_and_or_b32 v16, v8, s85, v0
	v_bfe_u32 v0, v23, 16, 1
	v_add3_u32 v0, v23, v0, s60
	v_bfe_u32 v8, v25, 16, 1
	v_lshrrev_b32_e32 v0, 16, v0
	v_add3_u32 v8, v25, v8, s60
	v_and_or_b32 v17, v8, s85, v0
	v_bfe_u32 v0, v27, 16, 1
	v_add3_u32 v0, v27, v0, s60
	v_bfe_u32 v8, v29, 16, 1
	v_lshrrev_b32_e32 v0, 16, v0
	v_add3_u32 v8, v29, v8, s60
	v_and_or_b32 v18, v8, s85, v0
	v_bfe_u32 v0, v31, 16, 1
	v_add3_u32 v0, v31, v0, s60
	v_bfe_u32 v8, v33, 16, 1
	v_lshrrev_b32_e32 v0, 16, v0
	v_add3_u32 v8, v33, v8, s60
	v_and_or_b32 v19, v8, s85, v0
	v_or_b32_e32 v8, s6, v11
	v_ashrrev_i32_e32 v9, 31, v8
	v_lshlrev_b64 v[8:9], 11, v[8:9]
	v_lshl_add_u64 v[8:9], v[6:7], 0, v[8:9]
	global_store_dwordx4 v[8:9], v[16:19], off sc1
	ds_read2_b32 v[8:9], v14 offset0:49 offset1:57
	ds_read2_b32 v[20:21], v14 offset0:16 offset1:24
	ds_read2_b32 v[22:23], v14 offset0:82 offset1:90
	ds_read2_b32 v[24:25], v14 offset0:115 offset1:123
	ds_read2_b32 v[26:27], v14 offset0:148 offset1:156
	ds_read2_b32 v[28:29], v14 offset0:181 offset1:189
	ds_read2_b32 v[30:31], v14 offset0:214 offset1:222
	ds_read2_b32 v[32:33], v14 offset0:247 offset1:255
	s_waitcnt lgkmcnt(7)
	v_bfe_u32 v15, v8, 16, 1
	s_waitcnt lgkmcnt(6)
	v_bfe_u32 v0, v20, 16, 1
	v_add3_u32 v0, v20, v0, s60
	v_lshrrev_b32_e32 v0, 16, v0
	v_add3_u32 v8, v8, v15, s60
	v_and_or_b32 v16, v8, s85, v0
	s_waitcnt lgkmcnt(5)
	v_bfe_u32 v0, v22, 16, 1
	v_add3_u32 v0, v22, v0, s60
	s_waitcnt lgkmcnt(4)
	v_bfe_u32 v8, v24, 16, 1
	v_lshrrev_b32_e32 v0, 16, v0
	v_add3_u32 v8, v24, v8, s60
	v_and_or_b32 v17, v8, s85, v0
	s_waitcnt lgkmcnt(3)
	v_bfe_u32 v0, v26, 16, 1
	v_add3_u32 v0, v26, v0, s60
	s_waitcnt lgkmcnt(2)
	v_bfe_u32 v8, v28, 16, 1
	v_lshrrev_b32_e32 v0, 16, v0
	v_add3_u32 v8, v28, v8, s60
	v_and_or_b32 v18, v8, s85, v0
	s_waitcnt lgkmcnt(1)
	v_bfe_u32 v0, v30, 16, 1
	v_add3_u32 v0, v30, v0, s60
	s_waitcnt lgkmcnt(0)
	v_bfe_u32 v8, v32, 16, 1
	v_lshrrev_b32_e32 v0, 16, v0
	v_add3_u32 v8, v32, v8, s60
	v_and_or_b32 v19, v8, s85, v0
	v_bfe_u32 v0, v21, 16, 1
	v_lshlrev_b64 v[34:35], 11, v[34:35]
	v_add3_u32 v0, v21, v0, s60
	v_bfe_u32 v8, v9, 16, 1
	v_lshl_add_u64 v[34:35], v[6:7], 0, v[34:35]
	v_lshrrev_b32_e32 v0, 16, v0
	v_add3_u32 v8, v9, v8, s60
	global_store_dwordx4 v[34:35], v[16:19], off sc1
	s_nop 1
	v_and_or_b32 v16, v8, s85, v0
	v_bfe_u32 v0, v23, 16, 1
	v_add3_u32 v0, v23, v0, s60
	v_bfe_u32 v8, v25, 16, 1
	v_lshrrev_b32_e32 v0, 16, v0
	v_add3_u32 v8, v25, v8, s60
	v_and_or_b32 v17, v8, s85, v0
	v_bfe_u32 v0, v27, 16, 1
	v_add3_u32 v0, v27, v0, s60
	v_bfe_u32 v8, v29, 16, 1
	v_lshrrev_b32_e32 v0, 16, v0
	v_add3_u32 v8, v29, v8, s60
	v_and_or_b32 v18, v8, s85, v0
	v_bfe_u32 v0, v31, 16, 1
	v_add3_u32 v0, v31, v0, s60
	v_bfe_u32 v8, v33, 16, 1
	v_lshrrev_b32_e32 v0, 16, v0
	v_add3_u32 v8, v33, v8, s60
	v_and_or_b32 v19, v8, s85, v0
	v_or_b32_e32 v8, s6, v13
	v_ashrrev_i32_e32 v9, 31, v8
	v_lshlrev_b64 v[8:9], 11, v[8:9]
	v_lshl_add_u64 v[6:7], v[6:7], 0, v[8:9]
	global_store_dwordx4 v[6:7], v[16:19], off sc1
	s_waitcnt lgkmcnt(0)
	s_branch .LBB0_447

.LBB0_494:
	s_andn2_saveexec_b64 s[0:1], s[10:11]
	s_cbranch_execz .LBB0_514
	s_mov_b64 s[10:11], exec
	s_waitcnt lgkmcnt(0)
	s_waitcnt vmcnt(0)
	v_mbcnt_lo_u32_b32 v0, s10, 0
	v_mbcnt_hi_u32_b32 v0, s11, v0
	v_cmp_eq_u32_e32 vcc, 0, v0
	s_and_saveexec_b64 s[12:13], vcc
	s_cbranch_execz .LBB0_497
	s_bcnt1_i32_b64 s0, s[10:11]
	v_mov_b32_e32 v3, s0
	v_mov_b32_e32 v4, 0xe803000
	global_atomic_add v3, v4, v3, s[6:7] offset:1024 sc0

.LBB0_625:
	s_cmpk_lt_u32 s0, 0x780
	s_cselect_b32 s4, s22, s21
	s_cmpk_lt_i32 s0, 0x200
	s_cselect_b32 s4, s20, s4
	s_add_i32 s5, s4, s0
	s_mul_hi_i32 s4, s5, 0x66666667
	s_lshr_b32 s10, s4, 31
	s_ashr_i32 s4, s4, 12
	s_add_i32 s4, s4, s10
	s_mul_i32 s10, s4, 0x2800
	s_sub_i32 s13, s5, s10
	s_cmpk_gt_i32 s13, 0x20ff
	s_mov_b64 s[10:11], -1
	s_cbranch_scc0 .LBB0_631
	s_cmpk_gt_u32 s13, 0x25ff
	s_cbranch_scc0 .LBB0_628
	s_load_dwordx2 s[10:11], s[6:7], 0x78
	s_ashr_i32 s5, s4, 31
	s_lshl_b64 s[14:15], s[4:5], 22
	v_lshlrev_b32_e32 v0, 2, v2
	v_mov_b32_e32 v41, v1
	s_waitcnt lgkmcnt(0)
	s_add_u32 s14, s10, s14
	s_addc_u32 s15, s11, s15
	s_lshl_b64 s[10:11], s[4:5], 21
	s_add_u32 s16, s1, s10
	s_addc_u32 s17, s2, s11
	s_lshl_b32 s5, s13, 1
	s_and_b32 s5, s5, 0x7fffffc0
	s_add_i32 s44, s5, 0xffffb400
	s_lshl_b32 s5, s13, 5
	s_and_b32 s5, s5, 0x3e0
	s_lshl_b32 s10, s5, 2
	s_add_u32 s10, s14, s10
	v_or_b32_e32 v40, s44, v3
	s_addc_u32 s11, s15, 0
	v_lshl_add_u64 v[42:43], s[10:11], 0, v[0:1]
	v_lshlrev_b64 v[6:7], 12, v[40:41]
	v_or_b32_e32 v0, 8, v40
	v_lshl_add_u64 v[6:7], v[42:43], 0, v[6:7]
	v_lshlrev_b64 v[16:17], 12, v[0:1]
	global_load_dwordx4 v[6:9], v[6:7], off nt
	v_lshl_add_u64 v[16:17], v[42:43], 0, v[16:17]
	v_or_b32_e32 v0, 16, v40
	global_load_dwordx4 v[16:19], v[16:17], off nt
	v_lshlrev_b64 v[20:21], 12, v[0:1]
	v_lshl_add_u64 v[20:21], v[42:43], 0, v[20:21]
	v_or_b32_e32 v0, 24, v40
	global_load_dwordx4 v[20:23], v[20:21], off nt
	v_lshlrev_b64 v[24:25], 12, v[0:1]
	v_lshl_add_u64 v[24:25], v[42:43], 0, v[24:25]
	v_or_b32_e32 v0, 32, v40
	global_load_dwordx4 v[24:27], v[24:25], off nt
	v_lshlrev_b64 v[28:29], 12, v[0:1]
	v_lshl_add_u64 v[28:29], v[42:43], 0, v[28:29]
	v_or_b32_e32 v0, 40, v40
	global_load_dwordx4 v[28:31], v[28:29], off nt
	v_lshlrev_b64 v[32:33], 12, v[0:1]
	v_lshl_add_u64 v[32:33], v[42:43], 0, v[32:33]
	v_or_b32_e32 v0, 48, v40
	global_load_dwordx4 v[32:35], v[32:33], off nt
	v_lshlrev_b64 v[36:37], 12, v[0:1]
	v_lshl_add_u64 v[36:37], v[42:43], 0, v[36:37]
	v_or_b32_e32 v0, 56, v40
	global_load_dwordx4 v[36:39], v[36:37], off nt
	v_lshlrev_b64 v[40:41], 12, v[0:1]
	v_lshl_add_u64 v[40:41], v[42:43], 0, v[40:41]
	global_load_dwordx4 v[40:43], v[40:41], off nt
	v_add_u32_e32 v0, v5, v10
	s_lshl_b64 s[10:11], s[44:45], 1
	s_add_u32 s10, s16, s10
	s_addc_u32 s11, s17, s11
	s_waitcnt vmcnt(0)
	ds_write2_b32 v0, v6, v7 offset1:1
	ds_write2_b32 v0, v8, v9 offset0:2 offset1:3
	v_add_u32_e32 v6, 0x420, v0
	ds_write2_b32 v6, v16, v17 offset1:1
	v_add_u32_e32 v6, 0x428, v0
	ds_write2_b32 v6, v18, v19 offset1:1
	v_add_u32_e32 v6, 0x840, v0
	ds_write2_b32 v6, v20, v21 offset1:1
	v_add_u32_e32 v6, 0x848, v0
	ds_write2_b32 v6, v22, v23 offset1:1
	v_add_u32_e32 v6, 0xc60, v0
	ds_write2_b32 v6, v24, v25 offset1:1
	v_add_u32_e32 v6, 0xc68, v0
	ds_write2_b32 v6, v26, v27 offset1:1
	v_add_u32_e32 v6, 0x1080, v0
	ds_write2_b32 v6, v28, v29 offset1:1
	v_add_u32_e32 v6, 0x1088, v0
	ds_write2_b32 v6, v30, v31 offset1:1
	v_add_u32_e32 v6, 0x14a0, v0
	ds_write2_b32 v6, v32, v33 offset1:1
	v_add_u32_e32 v6, 0x14a8, v0
	ds_write2_b32 v6, v34, v35 offset1:1
	v_add_u32_e32 v6, 0x18c0, v0
	ds_write2_b32 v6, v36, v37 offset1:1
	v_add_u32_e32 v6, 0x18c8, v0
	ds_write2_b32 v6, v38, v39 offset1:1
	v_add_u32_e32 v6, 0x1ce0, v0
	v_add_u32_e32 v0, 0x1ce8, v0
	ds_write2_b32 v6, v40, v41 offset1:1
	ds_write2_b32 v0, v42, v43 offset1:1
	s_waitcnt lgkmcnt(0)
	ds_read2_b32 v[8:9], v14 offset0:33 offset1:41
	ds_read2_b32 v[20:21], v14 offset1:8
	v_lshlrev_b32_e32 v0, 1, v4
	ds_read2_b32 v[22:23], v14 offset0:66 offset1:74
	ds_read2_b32 v[24:25], v14 offset0:99 offset1:107
	v_lshl_add_u64 v[6:7], s[10:11], 0, v[0:1]
	s_waitcnt lgkmcnt(3)
	v_bfe_u32 v15, v8, 16, 1
	s_waitcnt lgkmcnt(2)
	v_bfe_u32 v0, v20, 16, 1
	v_add3_u32 v0, v20, v0, s60
	v_lshrrev_b32_e32 v0, 16, v0
	v_add3_u32 v8, v8, v15, s60
	ds_read2_b32 v[26:27], v14 offset0:132 offset1:140
	ds_read2_b32 v[28:29], v14 offset0:165 offset1:173
	v_and_or_b32 v16, v8, s85, v0
	s_waitcnt lgkmcnt(3)
	v_bfe_u32 v0, v22, 16, 1
	v_add3_u32 v0, v22, v0, s60
	s_waitcnt lgkmcnt(2)
	v_bfe_u32 v8, v24, 16, 1
	v_lshrrev_b32_e32 v0, 16, v0
	v_add3_u32 v8, v24, v8, s60
	ds_read2_b32 v[30:31], v14 offset0:198 offset1:206
	ds_read2_b32 v[32:33], v14 offset0:231 offset1:239
	v_and_or_b32 v17, v8, s85, v0
	s_waitcnt lgkmcnt(3)
	v_bfe_u32 v0, v26, 16, 1
	v_add3_u32 v0, v26, v0, s60
	s_waitcnt lgkmcnt(2)
	v_bfe_u32 v8, v28, 16, 1
	v_lshrrev_b32_e32 v0, 16, v0
	v_add3_u32 v8, v28, v8, s60
	v_and_or_b32 v18, v8, s85, v0
	s_waitcnt lgkmcnt(1)
	v_bfe_u32 v0, v30, 16, 1
	v_add3_u32 v0, v30, v0, s60
	s_waitcnt lgkmcnt(0)
	v_bfe_u32 v8, v32, 16, 1
	v_lshrrev_b32_e32 v0, 16, v0
	v_add3_u32 v8, v32, v8, s60
	v_and_or_b32 v19, v8, s85, v0
	v_or_b32_e32 v0, s5, v3
	v_lshlrev_b32_e32 v0, 11, v0
	v_lshl_add_u64 v[34:35], v[6:7], 0, v[0:1]
	v_bfe_u32 v0, v21, 16, 1
	v_add3_u32 v0, v21, v0, s60
	v_bfe_u32 v8, v9, 16, 1
	v_lshrrev_b32_e32 v0, 16, v0
	v_add3_u32 v8, v9, v8, s60
	global_store_dwordx4 v[34:35], v[16:19], off sc1
	s_mov_b64 s[10:11], 0
	s_nop 0
	v_and_or_b32 v16, v8, s85, v0
	v_bfe_u32 v0, v23, 16, 1
	v_add3_u32 v0, v23, v0, s60
	v_bfe_u32 v8, v25, 16, 1
	v_lshrrev_b32_e32 v0, 16, v0
	v_add3_u32 v8, v25, v8, s60
	v_and_or_b32 v17, v8, s85, v0
	v_bfe_u32 v0, v27, 16, 1
	v_add3_u32 v0, v27, v0, s60
	v_bfe_u32 v8, v29, 16, 1
	v_lshrrev_b32_e32 v0, 16, v0
	v_add3_u32 v8, v29, v8, s60
	v_and_or_b32 v18, v8, s85, v0
	v_bfe_u32 v0, v31, 16, 1
	v_add3_u32 v0, v31, v0, s60
	v_bfe_u32 v8, v33, 16, 1
	v_lshrrev_b32_e32 v0, 16, v0
	v_add3_u32 v8, v33, v8, s60
	v_and_or_b32 v19, v8, s85, v0
	v_or_b32_e32 v0, s5, v11
	v_lshlrev_b32_e32 v0, 11, v0
	v_lshl_add_u64 v[8:9], v[6:7], 0, v[0:1]
	global_store_dwordx4 v[8:9], v[16:19], off sc1
	ds_read2_b32 v[8:9], v14 offset0:49 offset1:57
	ds_read2_b32 v[20:21], v14 offset0:16 offset1:24
	ds_read2_b32 v[22:23], v14 offset0:82 offset1:90
	ds_read2_b32 v[24:25], v14 offset0:115 offset1:123
	ds_read2_b32 v[26:27], v14 offset0:148 offset1:156
	ds_read2_b32 v[28:29], v14 offset0:181 offset1:189
	ds_read2_b32 v[30:31], v14 offset0:214 offset1:222
	ds_read2_b32 v[32:33], v14 offset0:247 offset1:255
	s_waitcnt lgkmcnt(7)
	v_bfe_u32 v15, v8, 16, 1
	s_waitcnt lgkmcnt(6)
	v_bfe_u32 v0, v20, 16, 1
	v_add3_u32 v0, v20, v0, s60
	v_lshrrev_b32_e32 v0, 16, v0
	v_add3_u32 v8, v8, v15, s60
	v_and_or_b32 v16, v8, s85, v0
	s_waitcnt lgkmcnt(5)
	v_bfe_u32 v0, v22, 16, 1
	v_add3_u32 v0, v22, v0, s60
	s_waitcnt lgkmcnt(4)
	v_bfe_u32 v8, v24, 16, 1
	v_lshrrev_b32_e32 v0, 16, v0
	v_add3_u32 v8, v24, v8, s60
	v_and_or_b32 v17, v8, s85, v0
	s_waitcnt lgkmcnt(3)
	v_bfe_u32 v0, v26, 16, 1
	v_add3_u32 v0, v26, v0, s60
	s_waitcnt lgkmcnt(2)
	v_bfe_u32 v8, v28, 16, 1
	v_lshrrev_b32_e32 v0, 16, v0
	v_add3_u32 v8, v28, v8, s60
	v_and_or_b32 v18, v8, s85, v0
	s_waitcnt lgkmcnt(1)
	v_bfe_u32 v0, v30, 16, 1
	v_add3_u32 v0, v30, v0, s60
	s_waitcnt lgkmcnt(0)
	v_bfe_u32 v8, v32, 16, 1
	v_lshrrev_b32_e32 v0, 16, v0
	v_add3_u32 v8, v32, v8, s60
	v_and_or_b32 v19, v8, s85, v0
	v_or_b32_e32 v0, s5, v12
	v_lshlrev_b32_e32 v0, 11, v0
	v_lshl_add_u64 v[34:35], v[6:7], 0, v[0:1]
	v_bfe_u32 v0, v21, 16, 1
	v_add3_u32 v0, v21, v0, s60
	v_bfe_u32 v8, v9, 16, 1
	v_lshrrev_b32_e32 v0, 16, v0
	v_add3_u32 v8, v9, v8, s60
	global_store_dwordx4 v[34:35], v[16:19], off sc1
	s_nop 1
	v_and_or_b32 v16, v8, s85, v0
	v_bfe_u32 v0, v23, 16, 1
	v_add3_u32 v0, v23, v0, s60
	v_bfe_u32 v8, v25, 16, 1
	v_lshrrev_b32_e32 v0, 16, v0
	v_add3_u32 v8, v25, v8, s60
	v_and_or_b32 v17, v8, s85, v0
	v_bfe_u32 v0, v27, 16, 1
	v_add3_u32 v0, v27, v0, s60
	v_bfe_u32 v8, v29, 16, 1
	v_lshrrev_b32_e32 v0, 16, v0
	v_add3_u32 v8, v29, v8, s60
	v_and_or_b32 v18, v8, s85, v0
	v_bfe_u32 v0, v31, 16, 1
	v_add3_u32 v0, v31, v0, s60
	v_bfe_u32 v8, v33, 16, 1
	v_lshrrev_b32_e32 v0, 16, v0
	v_add3_u32 v8, v33, v8, s60
	v_and_or_b32 v19, v8, s85, v0
	v_or_b32_e32 v0, s5, v13
	v_lshlrev_b32_e32 v0, 11, v0
	v_lshl_add_u64 v[6:7], v[6:7], 0, v[0:1]
	global_store_dwordx4 v[6:7], v[16:19], off sc1
	s_waitcnt lgkmcnt(0)
.LBB0_628:
	s_andn2_b64 vcc, exec, s[10:11]
	s_cbranch_vccnz .LBB0_630
	s_add_i32 s5, s13, 0xdf00
	s_and_b32 s10, s5, 0xffff
	s_mul_i32 s10, s10, 0xcccd
	s_lshr_b32 s14, s10, 16
	s_lshr_b32 s10, s10, 22
	s_mulk_i32 s10, 0x50
	s_sub_i32 s5, s5, s10
	s_load_dwordx2 s[10:11], s[6:7], 0x70
	s_mul_i32 s16, s4, 0xa00000
	s_mul_hi_i32 s15, s4, 0xa00000
	v_lshlrev_b32_e32 v0, 2, v2
	s_waitcnt lgkmcnt(0)
	s_add_u32 s10, s10, s16
	s_addc_u32 s11, s11, s15
	s_mul_i32 s16, s4, 0x500000
	s_mul_hi_i32 s15, s4, 0x500000
	s_add_u32 s16, s30, s16
	s_addc_u32 s15, s31, s15
	s_lshl_b32 s5, s5, 5
	s_and_b32 s5, s5, 0xffe0
	s_and_b32 s14, s14, 0xffc0
	s_lshl_b32 s17, s5, 2
	s_add_u32 s10, s10, s17
	v_or_b32_e32 v8, s14, v3
	s_addc_u32 s11, s11, 0
	v_lshl_add_u64 v[6:7], s[10:11], 0, v[0:1]
	v_mul_u32_u24_e32 v0, 0xa00, v8
	v_lshlrev_b32_e32 v0, 2, v0
	v_lshl_add_u64 v[40:41], v[6:7], 0, v[0:1]
	s_mov_b32 s10, 0x14000
	v_add_co_u32_e32 v16, vcc, s10, v40
	global_load_dwordx4 v[6:9], v[40:41], off nt
	s_nop 0
	v_addc_co_u32_e32 v17, vcc, 0, v41, vcc
	s_mov_b32 s10, 0x28000
	global_load_dwordx4 v[16:19], v[16:17], off nt
	v_add_co_u32_e32 v20, vcc, s10, v40
	s_mov_b32 s10, 0x3c000
	s_nop 0
	v_addc_co_u32_e32 v21, vcc, 0, v41, vcc
	global_load_dwordx4 v[20:23], v[20:21], off nt
	v_add_co_u32_e32 v24, vcc, s10, v40
	s_mov_b32 s10, 0x50000
	s_nop 0
	v_addc_co_u32_e32 v25, vcc, 0, v41, vcc
	global_load_dwordx4 v[24:27], v[24:25], off nt
	v_add_co_u32_e32 v28, vcc, s10, v40
	s_mov_b32 s10, 0x64000
	s_nop 0
	v_addc_co_u32_e32 v29, vcc, 0, v41, vcc
	global_load_dwordx4 v[28:31], v[28:29], off nt
	v_add_co_u32_e32 v32, vcc, s10, v40
	s_mov_b32 s10, 0x78000
	s_nop 0
	v_addc_co_u32_e32 v33, vcc, 0, v41, vcc
	global_load_dwordx4 v[32:35], v[32:33], off nt
	v_add_co_u32_e32 v36, vcc, s10, v40
	s_mov_b32 s10, 0x8c000
	s_nop 0
	v_addc_co_u32_e32 v37, vcc, 0, v41, vcc
	global_load_dwordx4 v[36:39], v[36:37], off nt
	v_add_co_u32_e32 v40, vcc, s10, v40
	v_add_u32_e32 v0, v5, v10
	s_nop 0
	v_addc_co_u32_e32 v41, vcc, 0, v41, vcc
	global_load_dwordx4 v[40:43], v[40:41], off nt
	s_lshl_b32 s10, s14, 1
	s_add_u32 s10, s16, s10
	s_addc_u32 s11, s15, 0
	s_waitcnt vmcnt(0)
	ds_write2_b32 v0, v6, v7 offset1:1
	ds_write2_b32 v0, v8, v9 offset0:2 offset1:3
	v_add_u32_e32 v6, 0x420, v0
	ds_write2_b32 v6, v16, v17 offset1:1
	v_add_u32_e32 v6, 0x428, v0
	ds_write2_b32 v6, v18, v19 offset1:1
	v_add_u32_e32 v6, 0x840, v0
	ds_write2_b32 v6, v20, v21 offset1:1
	v_add_u32_e32 v6, 0x848, v0
	ds_write2_b32 v6, v22, v23 offset1:1
	v_add_u32_e32 v6, 0xc60, v0
	ds_write2_b32 v6, v24, v25 offset1:1
	v_add_u32_e32 v6, 0xc68, v0
	ds_write2_b32 v6, v26, v27 offset1:1
	v_add_u32_e32 v6, 0x1080, v0
	ds_write2_b32 v6, v28, v29 offset1:1
	v_add_u32_e32 v6, 0x1088, v0
	ds_write2_b32 v6, v30, v31 offset1:1
	v_add_u32_e32 v6, 0x14a0, v0
	ds_write2_b32 v6, v32, v33 offset1:1
	v_add_u32_e32 v6, 0x14a8, v0
	ds_write2_b32 v6, v34, v35 offset1:1
	v_add_u32_e32 v6, 0x18c0, v0
	ds_write2_b32 v6, v36, v37 offset1:1
	v_add_u32_e32 v6, 0x18c8, v0
	ds_write2_b32 v6, v38, v39 offset1:1
	v_add_u32_e32 v6, 0x1ce0, v0
	v_add_u32_e32 v0, 0x1ce8, v0
	ds_write2_b32 v6, v40, v41 offset1:1
	ds_write2_b32 v0, v42, v43 offset1:1
	s_waitcnt lgkmcnt(0)
	ds_read2_b32 v[8:9], v14 offset0:33 offset1:41
	ds_read2_b32 v[20:21], v14 offset1:8
	v_lshlrev_b32_e32 v0, 1, v4
	ds_read2_b32 v[22:23], v14 offset0:66 offset1:74
	ds_read2_b32 v[24:25], v14 offset0:99 offset1:107
	v_lshl_add_u64 v[6:7], s[10:11], 0, v[0:1]
	s_waitcnt lgkmcnt(3)
	v_bfe_u32 v15, v8, 16, 1
	s_waitcnt lgkmcnt(2)
	v_bfe_u32 v0, v20, 16, 1
	v_add3_u32 v0, v20, v0, s60
	v_lshrrev_b32_e32 v0, 16, v0
	v_add3_u32 v8, v8, v15, s60
	ds_read2_b32 v[26:27], v14 offset0:132 offset1:140
	ds_read2_b32 v[28:29], v14 offset0:165 offset1:173
	v_and_or_b32 v16, v8, s85, v0
	s_waitcnt lgkmcnt(3)
	v_bfe_u32 v0, v22, 16, 1
	v_add3_u32 v0, v22, v0, s60
	s_waitcnt lgkmcnt(2)
	v_bfe_u32 v8, v24, 16, 1
	v_lshrrev_b32_e32 v0, 16, v0
	v_add3_u32 v8, v24, v8, s60
	ds_read2_b32 v[30:31], v14 offset0:198 offset1:206
	ds_read2_b32 v[32:33], v14 offset0:231 offset1:239
	v_and_or_b32 v17, v8, s85, v0
	s_waitcnt lgkmcnt(3)
	v_bfe_u32 v0, v26, 16, 1
	v_add3_u32 v0, v26, v0, s60
	s_waitcnt lgkmcnt(2)
	v_bfe_u32 v8, v28, 16, 1
	v_lshrrev_b32_e32 v0, 16, v0
	v_add3_u32 v8, v28, v8, s60
	v_and_or_b32 v18, v8, s85, v0
	s_waitcnt lgkmcnt(1)
	v_bfe_u32 v0, v30, 16, 1
	v_add3_u32 v0, v30, v0, s60
	s_waitcnt lgkmcnt(0)
	v_bfe_u32 v8, v32, 16, 1
	v_lshrrev_b32_e32 v0, 16, v0
	v_add3_u32 v8, v32, v8, s60
	v_and_or_b32 v19, v8, s85, v0
	v_or_b32_e32 v0, s5, v3
	v_lshlrev_b32_e32 v0, 11, v0
	v_lshl_add_u64 v[34:35], v[6:7], 0, v[0:1]
	v_bfe_u32 v0, v21, 16, 1
	v_add3_u32 v0, v21, v0, s60
	v_bfe_u32 v8, v9, 16, 1
	v_lshrrev_b32_e32 v0, 16, v0
	v_add3_u32 v8, v9, v8, s60
	global_store_dwordx4 v[34:35], v[16:19], off sc1
	s_nop 1
	v_and_or_b32 v16, v8, s85, v0
	v_bfe_u32 v0, v23, 16, 1
	v_add3_u32 v0, v23, v0, s60
	v_bfe_u32 v8, v25, 16, 1
	v_lshrrev_b32_e32 v0, 16, v0
	v_add3_u32 v8, v25, v8, s60
	v_and_or_b32 v17, v8, s85, v0
	v_bfe_u32 v0, v27, 16, 1
	v_add3_u32 v0, v27, v0, s60
	v_bfe_u32 v8, v29, 16, 1
	v_lshrrev_b32_e32 v0, 16, v0
	v_add3_u32 v8, v29, v8, s60
	v_and_or_b32 v18, v8, s85, v0
	v_bfe_u32 v0, v31, 16, 1
	v_add3_u32 v0, v31, v0, s60
	v_bfe_u32 v8, v33, 16, 1
	v_lshrrev_b32_e32 v0, 16, v0
	v_add3_u32 v8, v33, v8, s60
	v_and_or_b32 v19, v8, s85, v0
	v_or_b32_e32 v0, s5, v11
	v_lshlrev_b32_e32 v0, 11, v0
	v_lshl_add_u64 v[8:9], v[6:7], 0, v[0:1]
	global_store_dwordx4 v[8:9], v[16:19], off sc1
	ds_read2_b32 v[8:9], v14 offset0:49 offset1:57
	ds_read2_b32 v[20:21], v14 offset0:16 offset1:24
	ds_read2_b32 v[22:23], v14 offset0:82 offset1:90
	ds_read2_b32 v[24:25], v14 offset0:115 offset1:123
	ds_read2_b32 v[26:27], v14 offset0:148 offset1:156
	ds_read2_b32 v[28:29], v14 offset0:181 offset1:189
	ds_read2_b32 v[30:31], v14 offset0:214 offset1:222
	ds_read2_b32 v[32:33], v14 offset0:247 offset1:255
	s_waitcnt lgkmcnt(7)
	v_bfe_u32 v15, v8, 16, 1
	s_waitcnt lgkmcnt(6)
	v_bfe_u32 v0, v20, 16, 1
	v_add3_u32 v0, v20, v0, s60
	v_lshrrev_b32_e32 v0, 16, v0
	v_add3_u32 v8, v8, v15, s60
	v_and_or_b32 v16, v8, s85, v0
	s_waitcnt lgkmcnt(5)
	v_bfe_u32 v0, v22, 16, 1
	v_add3_u32 v0, v22, v0, s60
	s_waitcnt lgkmcnt(4)
	v_bfe_u32 v8, v24, 16, 1
	v_lshrrev_b32_e32 v0, 16, v0
	v_add3_u32 v8, v24, v8, s60
	v_and_or_b32 v17, v8, s85, v0
	s_waitcnt lgkmcnt(3)
	v_bfe_u32 v0, v26, 16, 1
	v_add3_u32 v0, v26, v0, s60
	s_waitcnt lgkmcnt(2)
	v_bfe_u32 v8, v28, 16, 1
	v_lshrrev_b32_e32 v0, 16, v0
	v_add3_u32 v8, v28, v8, s60
	v_and_or_b32 v18, v8, s85, v0
	s_waitcnt lgkmcnt(1)
	v_bfe_u32 v0, v30, 16, 1
	v_add3_u32 v0, v30, v0, s60
	s_waitcnt lgkmcnt(0)
	v_bfe_u32 v8, v32, 16, 1
	v_lshrrev_b32_e32 v0, 16, v0
	v_add3_u32 v8, v32, v8, s60
	v_and_or_b32 v19, v8, s85, v0
	v_or_b32_e32 v0, s5, v12
	v_lshlrev_b32_e32 v0, 11, v0
	v_lshl_add_u64 v[34:35], v[6:7], 0, v[0:1]
	v_bfe_u32 v0, v21, 16, 1
	v_add3_u32 v0, v21, v0, s60
	v_bfe_u32 v8, v9, 16, 1
	v_lshrrev_b32_e32 v0, 16, v0
	v_add3_u32 v8, v9, v8, s60
	global_store_dwordx4 v[34:35], v[16:19], off sc1
	s_nop 1
	v_and_or_b32 v16, v8, s85, v0
	v_bfe_u32 v0, v23, 16, 1
	v_add3_u32 v0, v23, v0, s60
	v_bfe_u32 v8, v25, 16, 1
	v_lshrrev_b32_e32 v0, 16, v0
	v_add3_u32 v8, v25, v8, s60
	v_and_or_b32 v17, v8, s85, v0
	v_bfe_u32 v0, v27, 16, 1
	v_add3_u32 v0, v27, v0, s60
	v_bfe_u32 v8, v29, 16, 1
	v_lshrrev_b32_e32 v0, 16, v0
	v_add3_u32 v8, v29, v8, s60
	v_and_or_b32 v18, v8, s85, v0
	v_bfe_u32 v0, v31, 16, 1
	v_add3_u32 v0, v31, v0, s60
	v_bfe_u32 v8, v33, 16, 1
	v_lshrrev_b32_e32 v0, 16, v0
	v_add3_u32 v8, v33, v8, s60
	v_and_or_b32 v19, v8, s85, v0
	v_or_b32_e32 v0, s5, v13
	v_lshlrev_b32_e32 v0, 11, v0
	v_lshl_add_u64 v[6:7], v[6:7], 0, v[0:1]
	global_store_dwordx4 v[6:7], v[16:19], off sc1
	s_waitcnt lgkmcnt(0)

.LBB0_631:
	s_andn2_b64 vcc, exec, s[10:11]
	s_cbranch_vccnz .LBB0_624
	s_mul_i32 s5, s13, 0xba3
	s_lshr_b32 s10, s5, 31
	s_ashr_i32 s5, s5, 22
	s_add_i32 s5, s5, s10
	s_mul_i32 s10, s5, 0x580
	s_sub_i32 s14, s13, s10
	v_add_u32_e32 v15, v5, v10
	s_mov_b64 s[10:11], -1
	s_cmpk_gt_i32 s13, 0x15ff
	s_sext_i32_i16 s13, s14
	v_lshlrev_b32_e32 v0, 2, v2
	v_add_u32_e32 v16, 0x420, v15
	v_add_u32_e32 v17, 0x428, v15
	v_add_u32_e32 v18, 0x840, v15
	v_add_u32_e32 v19, 0x848, v15
	v_add_u32_e32 v20, 0xc60, v15
	v_add_u32_e32 v21, 0xc68, v15
	v_add_u32_e32 v22, 0x1080, v15
	v_add_u32_e32 v23, 0x1088, v15
	v_add_u32_e32 v24, 0x14a0, v15
	v_add_u32_e32 v25, 0x14a8, v15
	v_add_u32_e32 v26, 0x18c0, v15
	v_add_u32_e32 v27, 0x18c8, v15
	v_add_u32_e32 v28, 0x1ce0, v15
	v_add_u32_e32 v29, 0x1ce8, v15
	v_lshlrev_b32_e32 v6, 1, v4
	s_cbranch_scc0 .LBB0_634
	s_load_dwordx2 s[10:11], s[6:7], 0x68
	s_lshl_b32 s15, s4, 1
	s_add_i32 s15, s15, s5
	s_add_i32 s15, s15, -4
	s_mul_i32 s17, s15, 0xb00000
	s_mul_hi_i32 s16, s15, 0xb00000
	s_waitcnt lgkmcnt(0)
	s_add_u32 s17, s10, s17
	s_addc_u32 s11, s11, s16
	s_mul_hi_i32 s10, s15, 0x580000
	s_mul_i32 s15, s15, 0x580000
	s_add_u32 s15, s3, s15
	s_addc_u32 s18, s12, s10
	s_lshl_b32 s10, s13, 1
	s_and_b32 s19, s10, 0xfc0
	s_lshl_b32 s10, s13, 5
	s_and_b32 s10, s10, 0x3e0
	s_lshl_b32 s16, s10, 2
	s_add_u32 s16, s17, s16
	v_or_b32_e32 v7, s19, v3
	s_addc_u32 s17, s11, 0
	v_lshl_add_u64 v[8:9], s[16:17], 0, v[0:1]
	v_lshlrev_b32_e32 v30, 12, v7
	v_mov_b32_e32 v31, v1
	v_lshl_add_u64 v[8:9], v[8:9], 0, v[30:31]
	s_mov_b32 s11, 0x8000
	global_load_dwordx4 v[30:33], v[8:9], off nt
	v_add_co_u32_e32 v34, vcc, s11, v8
	s_mov_b32 s11, 0x10000
	s_nop 0
	v_addc_co_u32_e32 v35, vcc, 0, v9, vcc
	global_load_dwordx4 v[34:37], v[34:35], off nt
	v_add_co_u32_e32 v38, vcc, s11, v8
	s_mov_b32 s11, 0x18000
	s_nop 0
	v_addc_co_u32_e32 v39, vcc, 0, v9, vcc
	global_load_dwordx4 v[38:41], v[38:39], off nt
	v_add_co_u32_e32 v42, vcc, s11, v8
	s_mov_b32 s11, 0x20000
	s_nop 0
	v_addc_co_u32_e32 v43, vcc, 0, v9, vcc
	global_load_dwordx4 v[42:45], v[42:43], off nt
	v_add_co_u32_e32 v46, vcc, s11, v8
	s_mov_b32 s11, 0x28000
	s_nop 0
	v_addc_co_u32_e32 v47, vcc, 0, v9, vcc
	global_load_dwordx4 v[46:49], v[46:47], off nt
	v_add_co_u32_e32 v50, vcc, s11, v8
	s_mov_b32 s11, 0x30000
	s_nop 0
	v_addc_co_u32_e32 v51, vcc, 0, v9, vcc
	global_load_dwordx4 v[50:53], v[50:51], off nt
	v_add_co_u32_e32 v54, vcc, s11, v8
	s_mov_b32 s11, 0x38000
	s_nop 0
	v_addc_co_u32_e32 v55, vcc, 0, v9, vcc
	global_load_dwordx4 v[54:57], v[54:55], off nt
	v_add_co_u32_e32 v8, vcc, s11, v8
	s_lshl_b32 s11, s19, 1
	s_nop 0
	v_addc_co_u32_e32 v9, vcc, 0, v9, vcc
	global_load_dwordx4 v[58:61], v[8:9], off nt
	s_add_u32 s16, s15, s11
	s_addc_u32 s17, s18, 0
	v_mov_b32_e32 v7, v1
	v_lshl_add_u64 v[8:9], s[16:17], 0, v[6:7]
	s_waitcnt vmcnt(0)
	ds_write2_b32 v15, v30, v31 offset1:1
	ds_write2_b32 v15, v32, v33 offset0:2 offset1:3
	ds_write2_b32 v16, v34, v35 offset1:1
	ds_write2_b32 v17, v36, v37 offset1:1
	ds_write2_b32 v18, v38, v39 offset1:1
	ds_write2_b32 v19, v40, v41 offset1:1
	ds_write2_b32 v20, v42, v43 offset1:1
	ds_write2_b32 v21, v44, v45 offset1:1
	ds_write2_b32 v22, v46, v47 offset1:1
	ds_write2_b32 v23, v48, v49 offset1:1
	ds_write2_b32 v24, v50, v51 offset1:1
	ds_write2_b32 v25, v52, v53 offset1:1
	ds_write2_b32 v26, v54, v55 offset1:1
	ds_write2_b32 v27, v56, v57 offset1:1
	ds_write2_b32 v28, v58, v59 offset1:1
	ds_write2_b32 v29, v60, v61 offset1:1
	s_waitcnt lgkmcnt(0)
	ds_read2_b32 v[34:35], v14 offset0:33 offset1:41
	ds_read2_b32 v[36:37], v14 offset1:8
	ds_read2_b32 v[38:39], v14 offset0:66 offset1:74
	ds_read2_b32 v[40:41], v14 offset0:99 offset1:107
	ds_read2_b32 v[42:43], v14 offset0:132 offset1:140
	ds_read2_b32 v[44:45], v14 offset0:165 offset1:173
	ds_read2_b32 v[46:47], v14 offset0:198 offset1:206
	ds_read2_b32 v[48:49], v14 offset0:231 offset1:239
	s_waitcnt lgkmcnt(7)
	v_bfe_u32 v30, v34, 16, 1
	s_waitcnt lgkmcnt(6)
	v_bfe_u32 v7, v36, 16, 1
	v_add3_u32 v7, v36, v7, s60
	v_lshrrev_b32_e32 v7, 16, v7
	v_add3_u32 v30, v34, v30, s60
	v_and_or_b32 v30, v30, s85, v7
	s_waitcnt lgkmcnt(5)
	v_bfe_u32 v7, v38, 16, 1
	v_add3_u32 v7, v38, v7, s60
	s_waitcnt lgkmcnt(4)
	v_bfe_u32 v31, v40, 16, 1
	v_lshrrev_b32_e32 v7, 16, v7
	v_add3_u32 v31, v40, v31, s60
	v_and_or_b32 v31, v31, s85, v7
	s_waitcnt lgkmcnt(3)
	v_bfe_u32 v7, v42, 16, 1
	v_add3_u32 v7, v42, v7, s60
	s_waitcnt lgkmcnt(2)
	v_bfe_u32 v32, v44, 16, 1
	v_lshrrev_b32_e32 v7, 16, v7
	v_add3_u32 v32, v44, v32, s60
	v_and_or_b32 v32, v32, s85, v7
	s_waitcnt lgkmcnt(1)
	v_bfe_u32 v7, v46, 16, 1
	v_add3_u32 v7, v46, v7, s60
	s_waitcnt lgkmcnt(0)
	v_bfe_u32 v33, v48, 16, 1
	v_lshrrev_b32_e32 v7, 16, v7
	v_add3_u32 v33, v48, v33, s60
	v_and_or_b32 v33, v33, s85, v7
	v_or_b32_e32 v7, s10, v3
	v_mul_u32_u24_e32 v7, 0xb00, v7
	v_lshlrev_b32_e32 v50, 1, v7
	v_mov_b32_e32 v51, v1
	v_lshl_add_u64 v[50:51], v[8:9], 0, v[50:51]
	v_bfe_u32 v7, v37, 16, 1
	global_store_dwordx4 v[50:51], v[30:33], off sc1
	v_add3_u32 v7, v37, v7, s60
	v_lshrrev_b32_e32 v7, 16, v7
	v_bfe_u32 v30, v35, 16, 1
	v_add3_u32 v30, v35, v30, s60
	v_and_or_b32 v30, v30, s85, v7
	v_bfe_u32 v7, v39, 16, 1
	v_add3_u32 v7, v39, v7, s60
	v_bfe_u32 v31, v41, 16, 1
	v_lshrrev_b32_e32 v7, 16, v7
	v_add3_u32 v31, v41, v31, s60
	v_and_or_b32 v31, v31, s85, v7
	v_bfe_u32 v7, v43, 16, 1
	v_add3_u32 v7, v43, v7, s60
	v_bfe_u32 v32, v45, 16, 1
	v_lshrrev_b32_e32 v7, 16, v7
	v_add3_u32 v32, v45, v32, s60
	v_and_or_b32 v32, v32, s85, v7
	v_bfe_u32 v7, v47, 16, 1
	v_add3_u32 v7, v47, v7, s60
	v_bfe_u32 v33, v49, 16, 1
	v_lshrrev_b32_e32 v7, 16, v7
	v_add3_u32 v33, v49, v33, s60
	v_and_or_b32 v33, v33, s85, v7
	v_or_b32_e32 v7, s10, v11
	v_mul_u32_u24_e32 v7, 0xb00, v7
	v_lshlrev_b32_e32 v34, 1, v7
	v_mov_b32_e32 v35, v1
	v_lshl_add_u64 v[34:35], v[8:9], 0, v[34:35]
	global_store_dwordx4 v[34:35], v[30:33], off sc1
	ds_read2_b32 v[34:35], v14 offset0:16 offset1:24
	ds_read2_b32 v[36:37], v14 offset0:49 offset1:57
	ds_read2_b32 v[38:39], v14 offset0:82 offset1:90
	ds_read2_b32 v[40:41], v14 offset0:115 offset1:123
	ds_read2_b32 v[42:43], v14 offset0:148 offset1:156
	ds_read2_b32 v[44:45], v14 offset0:181 offset1:189
	ds_read2_b32 v[46:47], v14 offset0:214 offset1:222
	ds_read2_b32 v[48:49], v14 offset0:247 offset1:255
	s_waitcnt lgkmcnt(7)
	v_bfe_u32 v7, v34, 16, 1
	v_add3_u32 v7, v34, v7, s60
	s_waitcnt lgkmcnt(6)
	v_bfe_u32 v30, v36, 16, 1
	v_lshrrev_b32_e32 v7, 16, v7
	v_add3_u32 v30, v36, v30, s60
	v_and_or_b32 v30, v30, s85, v7
	s_waitcnt lgkmcnt(5)
	v_bfe_u32 v7, v38, 16, 1
	v_add3_u32 v7, v38, v7, s60
	s_waitcnt lgkmcnt(4)
	v_bfe_u32 v31, v40, 16, 1
	v_lshrrev_b32_e32 v7, 16, v7
	v_add3_u32 v31, v40, v31, s60
	v_and_or_b32 v31, v31, s85, v7
	s_waitcnt lgkmcnt(3)
	v_bfe_u32 v7, v42, 16, 1
	v_add3_u32 v7, v42, v7, s60
	s_waitcnt lgkmcnt(2)
	v_bfe_u32 v32, v44, 16, 1
	v_lshrrev_b32_e32 v7, 16, v7
	v_add3_u32 v32, v44, v32, s60
	v_and_or_b32 v32, v32, s85, v7
	s_waitcnt lgkmcnt(1)
	v_bfe_u32 v7, v46, 16, 1
	v_add3_u32 v7, v46, v7, s60
	s_waitcnt lgkmcnt(0)
	v_bfe_u32 v33, v48, 16, 1
	v_lshrrev_b32_e32 v7, 16, v7
	v_add3_u32 v33, v48, v33, s60
	v_and_or_b32 v33, v33, s85, v7
	v_or_b32_e32 v7, s10, v12
	v_mul_u32_u24_e32 v7, 0xb00, v7
	v_lshlrev_b32_e32 v50, 1, v7
	v_mov_b32_e32 v51, v1
	v_lshl_add_u64 v[50:51], v[8:9], 0, v[50:51]
	v_bfe_u32 v7, v35, 16, 1
	global_store_dwordx4 v[50:51], v[30:33], off sc1
	v_add3_u32 v7, v35, v7, s60
	v_lshrrev_b32_e32 v7, 16, v7
	v_bfe_u32 v30, v37, 16, 1
	v_add3_u32 v30, v37, v30, s60
	v_and_or_b32 v30, v30, s85, v7
	v_bfe_u32 v7, v39, 16, 1
	v_add3_u32 v7, v39, v7, s60
	v_bfe_u32 v31, v41, 16, 1
	v_lshrrev_b32_e32 v7, 16, v7
	v_add3_u32 v31, v41, v31, s60
	v_and_or_b32 v31, v31, s85, v7
	v_bfe_u32 v7, v43, 16, 1
	v_add3_u32 v7, v43, v7, s60
	v_bfe_u32 v32, v45, 16, 1
	v_lshrrev_b32_e32 v7, 16, v7
	v_add3_u32 v32, v45, v32, s60
	v_and_or_b32 v32, v32, s85, v7
	v_bfe_u32 v7, v47, 16, 1
	v_add3_u32 v7, v47, v7, s60
	v_bfe_u32 v33, v49, 16, 1
	v_lshrrev_b32_e32 v7, 16, v7
	v_add3_u32 v33, v49, v33, s60
	v_and_or_b32 v33, v33, s85, v7
	v_or_b32_e32 v7, s10, v13
	v_mul_u32_u24_e32 v7, 0xb00, v7
	v_lshlrev_b32_e32 v34, 1, v7
	v_mov_b32_e32 v35, v1
	v_lshl_add_u64 v[8:9], v[8:9], 0, v[34:35]
	global_store_dwordx4 v[8:9], v[30:33], off sc1
	s_waitcnt lgkmcnt(0)
	s_mov_b64 s[10:11], 0
.LBB0_634:
	s_andn2_b64 vcc, exec, s[10:11]
	s_cbranch_vccnz .LBB0_624
	s_and_b32 s15, s5, 1
	s_and_b32 s10, s5, 0xffff
	s_cmp_lt_u32 s10, 2
	s_movk_i32 s10, 0x60
	s_cselect_b32 s10, 0x58, s10
	s_add_u32 s10, s6, s10
	s_addc_u32 s11, s7, 0
	s_load_dwordx2 s[10:11], s[10:11], 0x0
	s_lshl_b32 s4, s4, 1
	s_or_b32 s4, s15, s4
	s_mul_i32 s16, s4, 0xb00000
	s_mul_hi_i32 s15, s4, 0xb00000
	s_waitcnt lgkmcnt(0)
	s_add_u32 s17, s10, s16
	s_mulk_i32 s13, 0xba3
	s_addc_u32 s11, s11, s15
	s_lshr_b32 s4, s13, 31
	s_ashr_i32 s10, s13, 18
	s_add_i32 s4, s10, s4
	s_sext_i32_i16 s10, s4
	s_mulk_i32 s4, 0x58
	s_sub_i32 s4, s14, s4
	s_sext_i32_i16 s13, s4
	s_lshl_b32 s4, s13, 5
	s_add_u32 s16, s8, s16
	s_addc_u32 s18, s9, s15
	s_lshl_b32 s14, s10, 6
	s_lshl_b32 s10, s13, 6
	s_lshl_b32 s5, s5, 6
	s_and_b32 s10, s10, 0xffffff00
	s_and_b32 s5, s5, 0xffffff80
	s_add_i32 s10, s10, s5
	s_and_b32 s5, s4, 0x60
	s_or_b32 s10, s10, s5
	s_ashr_i32 s5, s4, 31
	s_lshl_b64 s[4:5], s[4:5], 2
	v_or_b32_e32 v7, s14, v3
	s_add_u32 s4, s17, s4
	s_addc_u32 s5, s11, s5
	v_mul_i32_i24_e32 v30, 0xb00, v7
	v_lshl_add_u64 v[8:9], s[4:5], 0, v[0:1]
	v_ashrrev_i32_e32 v31, 31, v30
	v_lshl_add_u64 v[8:9], v[30:31], 2, v[8:9]
	s_mov_b32 s4, 0x16000
	global_load_dwordx4 v[30:33], v[8:9], off nt
	v_add_co_u32_e32 v34, vcc, s4, v8
	s_mov_b32 s4, 0x2c000
	s_nop 0
	v_addc_co_u32_e32 v35, vcc, 0, v9, vcc
	global_load_dwordx4 v[34:37], v[34:35], off nt
	v_add_co_u32_e32 v38, vcc, s4, v8
	s_mov_b32 s4, 0x42000
	s_nop 0
	v_addc_co_u32_e32 v39, vcc, 0, v9, vcc
	global_load_dwordx4 v[38:41], v[38:39], off nt
	v_add_co_u32_e32 v42, vcc, s4, v8
	s_mov_b32 s4, 0x58000
	s_nop 0
	v_addc_co_u32_e32 v43, vcc, 0, v9, vcc
	global_load_dwordx4 v[42:45], v[42:43], off nt
	v_add_co_u32_e32 v46, vcc, s4, v8
	s_mov_b32 s4, 0x6e000
	s_nop 0
	v_addc_co_u32_e32 v47, vcc, 0, v9, vcc
	global_load_dwordx4 v[46:49], v[46:47], off nt
	v_add_co_u32_e32 v50, vcc, s4, v8
	s_mov_b32 s4, 0x84000
	s_nop 0
	v_addc_co_u32_e32 v51, vcc, 0, v9, vcc
	global_load_dwordx4 v[50:53], v[50:51], off nt
	v_add_co_u32_e32 v54, vcc, s4, v8
	s_mov_b32 s4, 0x9a000
	s_nop 0
	v_addc_co_u32_e32 v55, vcc, 0, v9, vcc
	global_load_dwordx4 v[54:57], v[54:55], off nt
	v_add_co_u32_e32 v8, vcc, s4, v8
	s_ashr_i32 s15, s14, 31
	s_nop 0
	v_addc_co_u32_e32 v9, vcc, 0, v9, vcc
	global_load_dwordx4 v[58:61], v[8:9], off nt
	s_lshl_b64 s[4:5], s[14:15], 1
	s_add_u32 s4, s16, s4
	s_addc_u32 s5, s18, s5
	v_mov_b32_e32 v7, v1
	v_lshl_add_u64 v[6:7], s[4:5], 0, v[6:7]
	s_waitcnt vmcnt(0)
	ds_write2_b32 v15, v30, v31 offset1:1
	ds_write2_b32 v15, v32, v33 offset0:2 offset1:3
	ds_write2_b32 v16, v34, v35 offset1:1
	ds_write2_b32 v17, v36, v37 offset1:1
	ds_write2_b32 v18, v38, v39 offset1:1
	ds_write2_b32 v19, v40, v41 offset1:1
	ds_write2_b32 v20, v42, v43 offset1:1
	ds_write2_b32 v21, v44, v45 offset1:1
	ds_write2_b32 v22, v46, v47 offset1:1
	ds_write2_b32 v23, v48, v49 offset1:1
	ds_write2_b32 v24, v50, v51 offset1:1
	ds_write2_b32 v25, v52, v53 offset1:1
	ds_write2_b32 v26, v54, v55 offset1:1
	ds_write2_b32 v27, v56, v57 offset1:1
	ds_write2_b32 v28, v58, v59 offset1:1
	ds_write2_b32 v29, v60, v61 offset1:1
	s_waitcnt lgkmcnt(0)
	ds_read2_b32 v[8:9], v14 offset0:33 offset1:41
	ds_read2_b32 v[20:21], v14 offset1:8
	ds_read2_b32 v[22:23], v14 offset0:66 offset1:74
	ds_read2_b32 v[24:25], v14 offset0:99 offset1:107
	ds_read2_b32 v[26:27], v14 offset0:132 offset1:140
	ds_read2_b32 v[28:29], v14 offset0:165 offset1:173
	ds_read2_b32 v[30:31], v14 offset0:198 offset1:206
	ds_read2_b32 v[32:33], v14 offset0:231 offset1:239
	s_waitcnt lgkmcnt(7)
	v_bfe_u32 v15, v8, 16, 1
	s_waitcnt lgkmcnt(6)
	v_bfe_u32 v0, v20, 16, 1
	v_add3_u32 v0, v20, v0, s60
	v_lshrrev_b32_e32 v0, 16, v0
	v_add3_u32 v8, v8, v15, s60
	v_and_or_b32 v16, v8, s85, v0
	s_waitcnt lgkmcnt(5)
	v_bfe_u32 v0, v22, 16, 1
	v_add3_u32 v0, v22, v0, s60
	s_waitcnt lgkmcnt(4)
	v_bfe_u32 v8, v24, 16, 1
	v_lshrrev_b32_e32 v0, 16, v0
	v_add3_u32 v8, v24, v8, s60
	v_and_or_b32 v17, v8, s85, v0
	s_waitcnt lgkmcnt(3)
	v_bfe_u32 v0, v26, 16, 1
	v_add3_u32 v0, v26, v0, s60
	s_waitcnt lgkmcnt(2)
	v_bfe_u32 v8, v28, 16, 1
	v_lshrrev_b32_e32 v0, 16, v0
	v_add3_u32 v8, v28, v8, s60
	v_and_or_b32 v18, v8, s85, v0
	s_waitcnt lgkmcnt(1)
	v_bfe_u32 v0, v30, 16, 1
	v_add3_u32 v0, v30, v0, s60
	s_waitcnt lgkmcnt(0)
	v_bfe_u32 v8, v32, 16, 1
	v_lshrrev_b32_e32 v0, 16, v0
	v_add3_u32 v8, v32, v8, s60
	v_or_b32_e32 v34, s10, v3
	v_and_or_b32 v19, v8, s85, v0
	v_ashrrev_i32_e32 v35, 31, v34
	v_bfe_u32 v0, v21, 16, 1
	v_lshlrev_b64 v[34:35], 11, v[34:35]
	v_add3_u32 v0, v21, v0, s60
	v_bfe_u32 v8, v9, 16, 1
	v_lshl_add_u64 v[34:35], v[6:7], 0, v[34:35]
	v_lshrrev_b32_e32 v0, 16, v0
	v_add3_u32 v8, v9, v8, s60
	global_store_dwordx4 v[34:35], v[16:19], off sc1
	v_or_b32_e32 v34, s10, v12
	v_ashrrev_i32_e32 v35, 31, v34
	v_and_or_b32 v16, v8, s85, v0
	v_bfe_u32 v0, v23, 16, 1
	v_add3_u32 v0, v23, v0, s60
	v_bfe_u32 v8, v25, 16, 1
	v_lshrrev_b32_e32 v0, 16, v0
	v_add3_u32 v8, v25, v8, s60
	v_and_or_b32 v17, v8, s85, v0
	v_bfe_u32 v0, v27, 16, 1
	v_add3_u32 v0, v27, v0, s60
	v_bfe_u32 v8, v29, 16, 1
	v_lshrrev_b32_e32 v0, 16, v0
	v_add3_u32 v8, v29, v8, s60
	v_and_or_b32 v18, v8, s85, v0
	v_bfe_u32 v0, v31, 16, 1
	v_add3_u32 v0, v31, v0, s60
	v_bfe_u32 v8, v33, 16, 1
	v_lshrrev_b32_e32 v0, 16, v0
	v_add3_u32 v8, v33, v8, s60
	v_and_or_b32 v19, v8, s85, v0
	v_or_b32_e32 v8, s10, v11
	v_ashrrev_i32_e32 v9, 31, v8
	v_lshlrev_b64 v[8:9], 11, v[8:9]
	v_lshl_add_u64 v[8:9], v[6:7], 0, v[8:9]
	global_store_dwordx4 v[8:9], v[16:19], off sc1
	ds_read2_b32 v[8:9], v14 offset0:49 offset1:57
	ds_read2_b32 v[20:21], v14 offset0:16 offset1:24
	ds_read2_b32 v[22:23], v14 offset0:82 offset1:90
	ds_read2_b32 v[24:25], v14 offset0:115 offset1:123
	ds_read2_b32 v[26:27], v14 offset0:148 offset1:156
	ds_read2_b32 v[28:29], v14 offset0:181 offset1:189
	ds_read2_b32 v[30:31], v14 offset0:214 offset1:222
	ds_read2_b32 v[32:33], v14 offset0:247 offset1:255
	s_waitcnt lgkmcnt(7)
	v_bfe_u32 v15, v8, 16, 1
	s_waitcnt lgkmcnt(6)
	v_bfe_u32 v0, v20, 16, 1
	v_add3_u32 v0, v20, v0, s60
	v_lshrrev_b32_e32 v0, 16, v0
	v_add3_u32 v8, v8, v15, s60
	v_and_or_b32 v16, v8, s85, v0
	s_waitcnt lgkmcnt(5)
	v_bfe_u32 v0, v22, 16, 1
	v_add3_u32 v0, v22, v0, s60
	s_waitcnt lgkmcnt(4)
	v_bfe_u32 v8, v24, 16, 1
	v_lshrrev_b32_e32 v0, 16, v0
	v_add3_u32 v8, v24, v8, s60
	v_and_or_b32 v17, v8, s85, v0
	s_waitcnt lgkmcnt(3)
	v_bfe_u32 v0, v26, 16, 1
	v_add3_u32 v0, v26, v0, s60
	s_waitcnt lgkmcnt(2)
	v_bfe_u32 v8, v28, 16, 1
	v_lshrrev_b32_e32 v0, 16, v0
	v_add3_u32 v8, v28, v8, s60
	v_and_or_b32 v18, v8, s85, v0
	s_waitcnt lgkmcnt(1)
	v_bfe_u32 v0, v30, 16, 1
	v_add3_u32 v0, v30, v0, s60
	s_waitcnt lgkmcnt(0)
	v_bfe_u32 v8, v32, 16, 1
	v_lshrrev_b32_e32 v0, 16, v0
	v_add3_u32 v8, v32, v8, s60
	v_and_or_b32 v19, v8, s85, v0
	v_bfe_u32 v0, v21, 16, 1
	v_lshlrev_b64 v[34:35], 11, v[34:35]
	v_add3_u32 v0, v21, v0, s60
	v_bfe_u32 v8, v9, 16, 1
	v_lshl_add_u64 v[34:35], v[6:7], 0, v[34:35]
	v_lshrrev_b32_e32 v0, 16, v0
	v_add3_u32 v8, v9, v8, s60
	global_store_dwordx4 v[34:35], v[16:19], off sc1
	s_nop 1
	v_and_or_b32 v16, v8, s85, v0
	v_bfe_u32 v0, v23, 16, 1
	v_add3_u32 v0, v23, v0, s60
	v_bfe_u32 v8, v25, 16, 1
	v_lshrrev_b32_e32 v0, 16, v0
	v_add3_u32 v8, v25, v8, s60
	v_and_or_b32 v17, v8, s85, v0
	v_bfe_u32 v0, v27, 16, 1
	v_add3_u32 v0, v27, v0, s60
	v_bfe_u32 v8, v29, 16, 1
	v_lshrrev_b32_e32 v0, 16, v0
	v_add3_u32 v8, v29, v8, s60
	v_and_or_b32 v18, v8, s85, v0
	v_bfe_u32 v0, v31, 16, 1
	v_add3_u32 v0, v31, v0, s60
	v_bfe_u32 v8, v33, 16, 1
	v_lshrrev_b32_e32 v0, 16, v0
	v_add3_u32 v8, v33, v8, s60
	v_and_or_b32 v19, v8, s85, v0
	v_or_b32_e32 v8, s10, v13
	v_ashrrev_i32_e32 v9, 31, v8
	v_lshlrev_b64 v[8:9], 11, v[8:9]
	v_lshl_add_u64 v[6:7], v[6:7], 0, v[8:9]
	global_store_dwordx4 v[6:7], v[16:19], off sc1
	s_waitcnt lgkmcnt(0)
	s_branch .LBB0_624
